# iteration 0 of every GEMM K loop peeled with SrcC=0 (no per-tile accumulator zeroing); branch islands for the 8 near-limit cross-phase branches
# speedup vs baseline: 1.0043x; 1.0043x over previous
.LBB0_158:
	s_ashr_i32 s45, s44, 31
	v_cmp_lt_i64_e32 vcc, s[48:49], v[140:141]
	s_lshl_b64 s[48:49], s[44:45], 19
	s_add_u32 s48, s2, s48
	s_addc_u32 s49, s3, s49
	s_and_b64 s[50:51], vcc, exec
	s_cselect_b32 s7, s49, s9
	s_cselect_b32 s45, s48, s8
	s_ashr_i32 s43, s42, 31
	s_lshl_b64 s[50:51], s[42:43], 19
	s_add_u32 s50, s10, s50
	s_addc_u32 s51, s11, s51
	s_and_b64 s[54:55], vcc, exec
	s_cselect_b32 s43, s51, s53
	s_cselect_b32 s65, s50, s52
	s_add_u32 s8, s8, 0x40080
	s_addc_u32 s9, s9, 0
	s_add_u32 s66, s52, 0x100

	s_addc_u32 s67, s53, 0
	s_mov_b32 s68, -2


	ds_read_b128 v[144:147], v156
	ds_read_b128 v[148:151], v156 offset:1024
	ds_read_b128 v[160:163], v156 offset:2048
	ds_read_b128 v[164:167], v156 offset:3072
	s_add_u32 s52, s8, 0xfffc0080
	s_addc_u32 s53, s9, -1
	s_cmp_eq_u32 s68, 12
	s_cselect_b32 s55, s7, s53
	s_cselect_b32 s54, s45, s52
	s_cselect_b32 s53, s43, s67
	s_cselect_b32 s52, s65, s66
	v_lshl_add_u64 v[200:201], s[8:9], 0, v[136:137]
	s_add_i32 m0, s33, 0xc000
	ds_read_b128 v[168:171], v157
	ds_read_b128 v[172:175], v157 offset:1024
	ds_read_b128 v[176:179], v157 offset:2048
	ds_read_b128 v[180:183], v157 offset:3072
	ds_read_b128 v[184:187], v157 offset:4096
	ds_read_b128 v[188:191], v157 offset:5120
	ds_read_b128 v[192:195], v157 offset:6144
	ds_read_b128 v[196:199], v157 offset:7168
	global_load_lds_dwordx4 v[200:201], off
	v_lshl_add_u64 v[200:201], s[8:9], 0, v[138:139]
	s_add_i32 m0, s33, 0xe000
	s_nop 0
	global_load_lds_dwordx4 v[200:201], off
	s_waitcnt lgkmcnt(8)
	s_barrier
	s_waitcnt lgkmcnt(0)
	s_setprio 1
	s_waitcnt lgkmcnt(0)
	v_mfma_f32_16x16x32_bf16 v[124:127], v[144:147], v[168:171], 0
	v_mfma_f32_16x16x32_bf16 v[120:123], v[160:163], v[168:171], 0
	v_mfma_f32_16x16x32_bf16 v[116:119], v[144:147], v[176:179], 0
	v_mfma_f32_16x16x32_bf16 v[108:111], v[160:163], v[176:179], 0
	v_mfma_f32_16x16x32_bf16 v[100:103], v[144:147], v[184:187], 0
	v_mfma_f32_16x16x32_bf16 v[92:95], v[160:163], v[184:187], 0
	v_mfma_f32_16x16x32_bf16 v[84:87], v[144:147], v[192:195], 0
	v_mfma_f32_16x16x32_bf16 v[76:79], v[160:163], v[192:195], 0
	v_mfma_f32_16x16x32_bf16 v[124:127], v[148:151], v[172:175], v[124:127]
	v_mfma_f32_16x16x32_bf16 v[120:123], v[164:167], v[172:175], v[120:123]
	v_mfma_f32_16x16x32_bf16 v[116:119], v[148:151], v[180:183], v[116:119]
	v_mfma_f32_16x16x32_bf16 v[108:111], v[164:167], v[180:183], v[108:111]
	v_mfma_f32_16x16x32_bf16 v[100:103], v[148:151], v[188:191], v[100:103]
	v_mfma_f32_16x16x32_bf16 v[92:95], v[164:167], v[188:191], v[92:95]
	v_mfma_f32_16x16x32_bf16 v[84:87], v[148:151], v[196:199], v[84:87]
	v_mfma_f32_16x16x32_bf16 v[76:79], v[164:167], v[196:199], v[76:79]
	s_setprio 0
	s_barrier
	s_add_i32 s69, s60, s1
	v_lshl_add_u64 v[218:219], s[52:53], 0, v[132:133]
	s_mov_b32 m0, s69
	ds_read_b128 v[200:203], v158
	ds_read_b128 v[206:209], v158 offset:1024
	ds_read_b128 v[210:213], v158 offset:2048
	ds_read_b128 v[214:217], v158 offset:3072
	global_load_lds_dwordx4 v[218:219], off
	v_lshl_add_u64 v[220:221], s[52:53], 0, v[128:129]
	s_add_i32 m0, s69, 0x2000
	s_nop 0
	global_load_lds_dwordx4 v[220:221], off
	s_barrier
	s_waitcnt lgkmcnt(0)
	s_setprio 1
	s_waitcnt lgkmcnt(0)
	v_mfma_f32_16x16x32_bf16 v[112:115], v[200:203], v[168:171], 0
	v_mfma_f32_16x16x32_bf16 v[104:107], v[210:213], v[168:171], 0
	v_mfma_f32_16x16x32_bf16 v[96:99], v[200:203], v[176:179], 0
	v_mfma_f32_16x16x32_bf16 v[88:91], v[210:213], v[176:179], 0
	v_mfma_f32_16x16x32_bf16 v[80:83], v[200:203], v[184:187], 0
	v_mfma_f32_16x16x32_bf16 v[72:75], v[210:213], v[184:187], 0
	v_mfma_f32_16x16x32_bf16 v[68:71], v[200:203], v[192:195], 0
	v_mfma_f32_16x16x32_bf16 v[64:67], v[210:213], v[192:195], 0
	v_mfma_f32_16x16x32_bf16 v[112:115], v[206:209], v[172:175], v[112:115]
	v_mfma_f32_16x16x32_bf16 v[104:107], v[214:217], v[172:175], v[104:107]
	v_mfma_f32_16x16x32_bf16 v[96:99], v[206:209], v[180:183], v[96:99]
	v_mfma_f32_16x16x32_bf16 v[88:91], v[214:217], v[180:183], v[88:91]
	v_mfma_f32_16x16x32_bf16 v[80:83], v[206:209], v[188:191], v[80:83]
	v_mfma_f32_16x16x32_bf16 v[72:75], v[214:217], v[188:191], v[72:75]
	v_mfma_f32_16x16x32_bf16 v[68:71], v[206:209], v[196:199], v[68:71]
	v_mfma_f32_16x16x32_bf16 v[64:67], v[214:217], v[196:199], v[64:67]
	s_setprio 0
	s_mov_b32 m0, s33
	v_lshl_add_u64 v[222:223], s[54:55], 0, v[134:135]
	s_barrier
	ds_read_b128 v[168:171], v157 offset:16384
	ds_read_b128 v[172:175], v157 offset:17408
	ds_read_b128 v[176:179], v157 offset:18432
	ds_read_b128 v[180:183], v157 offset:19456
	ds_read_b128 v[184:187], v157 offset:20480
	ds_read_b128 v[188:191], v157 offset:21504
	ds_read_b128 v[192:195], v157 offset:22528
	ds_read_b128 v[196:199], v157 offset:23552
	global_load_lds_dwordx4 v[222:223], off
	v_lshl_add_u64 v[224:225], s[54:55], 0, v[130:131]
	s_mov_b32 m0, s34
	s_nop 0
	global_load_lds_dwordx4 v[224:225], off
	s_barrier
	s_waitcnt lgkmcnt(0)
	s_setprio 1
	s_waitcnt lgkmcnt(0)
	v_mfma_f32_16x16x32_bf16 v[60:63], v[144:147], v[168:171], 0
	v_mfma_f32_16x16x32_bf16 v[56:59], v[160:163], v[168:171], 0
	v_mfma_f32_16x16x32_bf16 v[52:55], v[144:147], v[176:179], 0
	v_mfma_f32_16x16x32_bf16 v[44:47], v[160:163], v[176:179], 0
	v_mfma_f32_16x16x32_bf16 v[36:39], v[144:147], v[184:187], 0
	v_mfma_f32_16x16x32_bf16 v[28:31], v[160:163], v[184:187], 0
	v_mfma_f32_16x16x32_bf16 v[20:23], v[144:147], v[192:195], 0
	v_mfma_f32_16x16x32_bf16 v[12:15], v[160:163], v[192:195], 0
	v_mfma_f32_16x16x32_bf16 v[60:63], v[148:151], v[172:175], v[60:63]
	v_mfma_f32_16x16x32_bf16 v[56:59], v[164:167], v[172:175], v[56:59]
	v_mfma_f32_16x16x32_bf16 v[52:55], v[148:151], v[180:183], v[52:55]
	v_mfma_f32_16x16x32_bf16 v[44:47], v[164:167], v[180:183], v[44:47]
	v_mfma_f32_16x16x32_bf16 v[36:39], v[148:151], v[188:191], v[36:39]
	v_mfma_f32_16x16x32_bf16 v[28:31], v[164:167], v[188:191], v[28:31]
	v_mfma_f32_16x16x32_bf16 v[20:23], v[148:151], v[196:199], v[20:23]
	v_mfma_f32_16x16x32_bf16 v[12:15], v[164:167], v[196:199], v[12:15]
	s_setprio 0
	s_barrier
	s_add_u32 s70, s52, 0x40000
	s_addc_u32 s71, s53, 0
	s_add_i32 s69, s61, s1
	v_lshl_add_u64 v[144:145], s[70:71], 0, v[132:133]
	s_mov_b32 m0, s69
	s_nop 0
	global_load_lds_dwordx4 v[144:145], off
	v_lshl_add_u64 v[144:145], s[70:71], 0, v[128:129]
	s_add_i32 m0, s69, 0x2000
	s_nop 0
	global_load_lds_dwordx4 v[144:145], off
	s_waitcnt vmcnt(6)
	s_barrier
	s_setprio 1
	v_mfma_f32_16x16x32_bf16 v[48:51], v[200:203], v[168:171], 0
	v_mfma_f32_16x16x32_bf16 v[40:43], v[210:213], v[168:171], 0
	v_mfma_f32_16x16x32_bf16 v[32:35], v[200:203], v[176:179], 0
	v_mfma_f32_16x16x32_bf16 v[24:27], v[210:213], v[176:179], 0
	v_mfma_f32_16x16x32_bf16 v[16:19], v[200:203], v[184:187], 0
	v_mfma_f32_16x16x32_bf16 v[8:11], v[210:213], v[184:187], 0
	v_mfma_f32_16x16x32_bf16 v[4:7], v[200:203], v[192:195], 0
	v_mfma_f32_16x16x32_bf16 v[0:3], v[210:213], v[192:195], 0
	v_mfma_f32_16x16x32_bf16 v[48:51], v[206:209], v[172:175], v[48:51]
	v_mfma_f32_16x16x32_bf16 v[40:43], v[214:217], v[172:175], v[40:43]
	v_mfma_f32_16x16x32_bf16 v[32:35], v[206:209], v[180:183], v[32:35]
	v_mfma_f32_16x16x32_bf16 v[24:27], v[214:217], v[180:183], v[24:27]
	v_mfma_f32_16x16x32_bf16 v[16:19], v[206:209], v[188:191], v[16:19]
	v_mfma_f32_16x16x32_bf16 v[8:11], v[214:217], v[188:191], v[8:11]
	v_mfma_f32_16x16x32_bf16 v[4:7], v[206:209], v[196:199], v[4:7]
	v_mfma_f32_16x16x32_bf16 v[0:3], v[214:217], v[196:199], v[0:3]
	s_setprio 0
	s_add_i32 s69, 0, 0x18000
	v_add_u32_e32 v164, s69, v154
	s_barrier
	ds_read_b128 v[144:147], v164
	ds_read_b128 v[148:151], v164 offset:1024
	ds_read_b128 v[160:163], v164 offset:2048
	ds_read_b128 v[164:167], v164 offset:3072
	s_add_u32 s54, s54, 0x40000
	s_addc_u32 s55, s55, 0
	s_mov_b32 m0, s35
	v_lshl_add_u64 v[200:201], s[54:55], 0, v[134:135]
	ds_read_b128 v[168:171], v157 offset:32768
	ds_read_b128 v[172:175], v157 offset:33792
	ds_read_b128 v[176:179], v157 offset:34816
	ds_read_b128 v[180:183], v157 offset:35840
	ds_read_b128 v[184:187], v157 offset:36864
	ds_read_b128 v[188:191], v157 offset:37888
	ds_read_b128 v[192:195], v157 offset:38912
	ds_read_b128 v[196:199], v157 offset:39936
	global_load_lds_dwordx4 v[200:201], off
	v_lshl_add_u64 v[200:201], s[54:55], 0, v[130:131]
	s_mov_b32 m0, s46
	s_nop 0
	global_load_lds_dwordx4 v[200:201], off
	s_waitcnt lgkmcnt(8)
	s_barrier
	s_waitcnt lgkmcnt(0)
	s_setprio 1
	s_waitcnt lgkmcnt(0)
	v_mfma_f32_16x16x32_bf16 v[124:127], v[144:147], v[168:171], v[124:127]
	v_mfma_f32_16x16x32_bf16 v[120:123], v[160:163], v[168:171], v[120:123]
	v_mfma_f32_16x16x32_bf16 v[116:119], v[144:147], v[176:179], v[116:119]
	v_mfma_f32_16x16x32_bf16 v[108:111], v[160:163], v[176:179], v[108:111]
	v_mfma_f32_16x16x32_bf16 v[100:103], v[144:147], v[184:187], v[100:103]
	v_mfma_f32_16x16x32_bf16 v[92:95], v[160:163], v[184:187], v[92:95]
	v_mfma_f32_16x16x32_bf16 v[84:87], v[144:147], v[192:195], v[84:87]
	v_mfma_f32_16x16x32_bf16 v[76:79], v[160:163], v[192:195], v[76:79]
	v_mfma_f32_16x16x32_bf16 v[124:127], v[148:151], v[172:175], v[124:127]
	v_mfma_f32_16x16x32_bf16 v[120:123], v[164:167], v[172:175], v[120:123]
	v_mfma_f32_16x16x32_bf16 v[116:119], v[148:151], v[180:183], v[116:119]
	v_mfma_f32_16x16x32_bf16 v[108:111], v[164:167], v[180:183], v[108:111]
	v_mfma_f32_16x16x32_bf16 v[100:103], v[148:151], v[188:191], v[100:103]
	v_mfma_f32_16x16x32_bf16 v[92:95], v[164:167], v[188:191], v[92:95]
	v_mfma_f32_16x16x32_bf16 v[84:87], v[148:151], v[196:199], v[84:87]
	v_mfma_f32_16x16x32_bf16 v[76:79], v[164:167], v[196:199], v[76:79]
	s_setprio 0
	s_barrier
	s_add_i32 s54, 0, 0x1c000
	s_add_i32 s55, s69, s1
	v_add_u32_e32 v205, s54, v154
	v_lshl_add_u64 v[218:219], v[218:219], 0, s[40:41]
	s_mov_b32 m0, s55
	ds_read_b128 v[200:203], v205
	ds_read_b128 v[206:209], v205 offset:1024
	ds_read_b128 v[210:213], v205 offset:2048
	ds_read_b128 v[214:217], v205 offset:3072
	global_load_lds_dwordx4 v[218:219], off
	v_lshl_add_u64 v[218:219], v[220:221], 0, s[40:41]
	s_add_i32 m0, s55, 0x2000
	s_nop 0
	global_load_lds_dwordx4 v[218:219], off
	s_barrier
	s_waitcnt lgkmcnt(0)
	s_setprio 1
	s_waitcnt lgkmcnt(0)
	v_mfma_f32_16x16x32_bf16 v[112:115], v[200:203], v[168:171], v[112:115]
	v_mfma_f32_16x16x32_bf16 v[104:107], v[210:213], v[168:171], v[104:107]
	v_mfma_f32_16x16x32_bf16 v[96:99], v[200:203], v[176:179], v[96:99]
	v_mfma_f32_16x16x32_bf16 v[88:91], v[210:213], v[176:179], v[88:91]
	v_mfma_f32_16x16x32_bf16 v[80:83], v[200:203], v[184:187], v[80:83]
	v_mfma_f32_16x16x32_bf16 v[72:75], v[210:213], v[184:187], v[72:75]
	v_mfma_f32_16x16x32_bf16 v[68:71], v[200:203], v[192:195], v[68:71]
	v_mfma_f32_16x16x32_bf16 v[64:67], v[210:213], v[192:195], v[64:67]
	v_mfma_f32_16x16x32_bf16 v[112:115], v[206:209], v[172:175], v[112:115]
	v_mfma_f32_16x16x32_bf16 v[104:107], v[214:217], v[172:175], v[104:107]
	v_mfma_f32_16x16x32_bf16 v[96:99], v[206:209], v[180:183], v[96:99]
	v_mfma_f32_16x16x32_bf16 v[88:91], v[214:217], v[180:183], v[88:91]
	v_mfma_f32_16x16x32_bf16 v[80:83], v[206:209], v[188:191], v[80:83]
	v_mfma_f32_16x16x32_bf16 v[72:75], v[214:217], v[188:191], v[72:75]
	v_mfma_f32_16x16x32_bf16 v[68:71], v[206:209], v[196:199], v[68:71]
	v_mfma_f32_16x16x32_bf16 v[64:67], v[214:217], v[196:199], v[64:67]
	s_setprio 0
	s_mov_b32 m0, s56
	v_lshl_add_u64 v[218:219], v[222:223], 0, s[40:41]
	s_barrier
	ds_read_b128 v[168:171], v157 offset:49152
	ds_read_b128 v[172:175], v157 offset:50176
	ds_read_b128 v[176:179], v157 offset:51200
	ds_read_b128 v[180:183], v157 offset:52224
	ds_read_b128 v[184:187], v157 offset:53248
	ds_read_b128 v[188:191], v157 offset:54272
	ds_read_b128 v[192:195], v157 offset:55296
	ds_read_b128 v[196:199], v157 offset:56320
	global_load_lds_dwordx4 v[218:219], off
	v_lshl_add_u64 v[218:219], v[224:225], 0, s[40:41]
	s_mov_b32 m0, s57
	s_nop 0
	global_load_lds_dwordx4 v[218:219], off
	s_barrier
	s_waitcnt lgkmcnt(0)
	s_setprio 1
	s_waitcnt lgkmcnt(0)
	v_mfma_f32_16x16x32_bf16 v[60:63], v[144:147], v[168:171], v[60:63]
	v_mfma_f32_16x16x32_bf16 v[56:59], v[160:163], v[168:171], v[56:59]
	v_mfma_f32_16x16x32_bf16 v[52:55], v[144:147], v[176:179], v[52:55]
	v_mfma_f32_16x16x32_bf16 v[44:47], v[160:163], v[176:179], v[44:47]
	v_mfma_f32_16x16x32_bf16 v[36:39], v[144:147], v[184:187], v[36:39]
	v_mfma_f32_16x16x32_bf16 v[28:31], v[160:163], v[184:187], v[28:31]
	v_mfma_f32_16x16x32_bf16 v[20:23], v[144:147], v[192:195], v[20:23]
	v_mfma_f32_16x16x32_bf16 v[12:15], v[160:163], v[192:195], v[12:15]
	v_mfma_f32_16x16x32_bf16 v[60:63], v[148:151], v[172:175], v[60:63]
	v_mfma_f32_16x16x32_bf16 v[56:59], v[164:167], v[172:175], v[56:59]
	v_mfma_f32_16x16x32_bf16 v[52:55], v[148:151], v[180:183], v[52:55]
	v_mfma_f32_16x16x32_bf16 v[44:47], v[164:167], v[180:183], v[44:47]
	v_mfma_f32_16x16x32_bf16 v[36:39], v[148:151], v[188:191], v[36:39]
	v_mfma_f32_16x16x32_bf16 v[28:31], v[164:167], v[188:191], v[28:31]
	v_mfma_f32_16x16x32_bf16 v[20:23], v[148:151], v[196:199], v[20:23]
	v_mfma_f32_16x16x32_bf16 v[12:15], v[164:167], v[196:199], v[12:15]
	s_setprio 0
	s_barrier
	s_add_u32 s52, s52, 0x40080
	s_addc_u32 s53, s53, 0
	s_add_i32 s54, s54, s1
	v_lshl_add_u64 v[144:145], s[52:53], 0, v[132:133]
	s_mov_b32 m0, s54
	s_nop 0
	global_load_lds_dwordx4 v[144:145], off
	v_lshl_add_u64 v[144:145], s[52:53], 0, v[128:129]
	s_add_i32 m0, s54, 0x2000
	s_nop 0
	global_load_lds_dwordx4 v[144:145], off
	s_waitcnt vmcnt(6)
	s_barrier
	s_setprio 1
	v_mfma_f32_16x16x32_bf16 v[48:51], v[200:203], v[168:171], v[48:51]
	v_mfma_f32_16x16x32_bf16 v[40:43], v[210:213], v[168:171], v[40:43]
	v_mfma_f32_16x16x32_bf16 v[32:35], v[200:203], v[176:179], v[32:35]
	v_mfma_f32_16x16x32_bf16 v[24:27], v[210:213], v[176:179], v[24:27]
	v_mfma_f32_16x16x32_bf16 v[16:19], v[200:203], v[184:187], v[16:19]
	v_mfma_f32_16x16x32_bf16 v[8:11], v[210:213], v[184:187], v[8:11]
	v_mfma_f32_16x16x32_bf16 v[4:7], v[200:203], v[192:195], v[4:7]
	v_mfma_f32_16x16x32_bf16 v[0:3], v[210:213], v[192:195], v[0:3]
	v_mfma_f32_16x16x32_bf16 v[48:51], v[206:209], v[172:175], v[48:51]
	v_mfma_f32_16x16x32_bf16 v[40:43], v[214:217], v[172:175], v[40:43]
	v_mfma_f32_16x16x32_bf16 v[32:35], v[206:209], v[180:183], v[32:35]
	v_mfma_f32_16x16x32_bf16 v[24:27], v[214:217], v[180:183], v[24:27]
	v_mfma_f32_16x16x32_bf16 v[16:19], v[206:209], v[188:191], v[16:19]
	v_mfma_f32_16x16x32_bf16 v[8:11], v[214:217], v[188:191], v[8:11]
	v_mfma_f32_16x16x32_bf16 v[4:7], v[206:209], v[196:199], v[4:7]
	v_mfma_f32_16x16x32_bf16 v[0:3], v[214:217], v[196:199], v[0:3]
	s_setprio 0
	s_add_i32 s68, s68, 2
	s_add_u32 s8, s8, 0x100
	s_addc_u32 s9, s9, 0
	s_add_u32 s66, s66, 0x100
	s_addc_u32 s67, s67, 0
	s_cmp_gt_u32 s68, 13
	s_barrier

.Lisl_1158:
	s_branch .LBB0_1158

.LBB0_899:
	s_ashr_i32 s31, s30, 31
	v_cmp_lt_i64_e32 vcc, s[36:37], v[188:189]
	s_lshl_b64 s[36:37], s[30:31], 19
	s_add_u32 s36, s12, s36
	s_addc_u32 s37, s13, s37
	s_and_b64 s[38:39], vcc, exec
	s_cselect_b32 s31, s37, s55
	s_cselect_b32 s51, s36, s54
	s_ashr_i32 s27, s26, 31
	s_lshl_b64 s[38:39], s[26:27], 19
	s_add_u32 s38, s1, s38
	s_addc_u32 s39, s2, s39
	s_and_b64 s[58:59], vcc, exec
	s_cselect_b32 s27, s39, s57
	s_cselect_b32 s53, s38, s56
	s_add_u32 s54, s54, 0x40080
	s_addc_u32 s55, s55, 0
	s_add_u32 s60, s56, 0x100

	s_addc_u32 s61, s57, 0
	s_mov_b32 s62, -2
	s_waitcnt lgkmcnt(0)


	ds_read_b128 v[128:131], v209
	ds_read_b128 v[132:135], v209 offset:1024
	ds_read_b128 v[136:139], v209 offset:2048
	ds_read_b128 v[140:143], v209 offset:3072
	s_add_u32 s56, s54, 0xfffc0080
	s_addc_u32 s57, s55, -1
	s_cmp_eq_u32 s62, 12
	s_cselect_b32 s59, s31, s57
	s_cselect_b32 s58, s51, s56
	s_cselect_b32 s57, s27, s61
	s_cselect_b32 s56, s53, s60
	v_lshl_add_u64 v[192:193], s[54:55], 0, v[184:185]
	s_add_i32 m0, s21, 0xc000
	ds_read_b128 v[144:147], v210
	ds_read_b128 v[148:151], v210 offset:1024
	ds_read_b128 v[152:155], v210 offset:2048
	ds_read_b128 v[156:159], v210 offset:3072
	ds_read_b128 v[160:163], v210 offset:4096
	ds_read_b128 v[164:167], v210 offset:5120
	ds_read_b128 v[168:171], v210 offset:6144
	ds_read_b128 v[172:175], v210 offset:7168
	global_load_lds_dwordx4 v[192:193], off
	v_lshl_add_u64 v[192:193], s[54:55], 0, v[186:187]
	s_add_i32 m0, s21, 0xe000
	s_nop 0
	global_load_lds_dwordx4 v[192:193], off
	s_waitcnt lgkmcnt(8)
	s_barrier
	s_waitcnt lgkmcnt(0)
	s_setprio 1
	s_waitcnt lgkmcnt(0)
	v_mfma_f32_16x16x32_bf16 v[124:127], v[128:131], v[144:147], 0
	v_mfma_f32_16x16x32_bf16 v[120:123], v[136:139], v[144:147], 0
	v_mfma_f32_16x16x32_bf16 v[108:111], v[128:131], v[152:155], 0
	v_mfma_f32_16x16x32_bf16 v[104:107], v[136:139], v[152:155], 0
	v_mfma_f32_16x16x32_bf16 v[92:95], v[128:131], v[160:163], 0
	v_mfma_f32_16x16x32_bf16 v[88:91], v[136:139], v[160:163], 0
	v_mfma_f32_16x16x32_bf16 v[76:79], v[128:131], v[168:171], 0
	v_mfma_f32_16x16x32_bf16 v[72:75], v[136:139], v[168:171], 0
	v_mfma_f32_16x16x32_bf16 v[124:127], v[132:135], v[148:151], v[124:127]
	v_mfma_f32_16x16x32_bf16 v[120:123], v[140:143], v[148:151], v[120:123]
	v_mfma_f32_16x16x32_bf16 v[108:111], v[132:135], v[156:159], v[108:111]
	v_mfma_f32_16x16x32_bf16 v[104:107], v[140:143], v[156:159], v[104:107]
	v_mfma_f32_16x16x32_bf16 v[92:95], v[132:135], v[164:167], v[92:95]
	v_mfma_f32_16x16x32_bf16 v[88:91], v[140:143], v[164:167], v[88:91]
	v_mfma_f32_16x16x32_bf16 v[76:79], v[132:135], v[172:175], v[76:79]
	v_mfma_f32_16x16x32_bf16 v[72:75], v[140:143], v[172:175], v[72:75]
	s_setprio 0
	s_barrier
	s_add_i32 s63, s48, s20
	v_lshl_add_u64 v[216:217], s[56:57], 0, v[178:179]
	s_mov_b32 m0, s63
	ds_read_b128 v[192:195], v211
	ds_read_b128 v[196:199], v211 offset:1024
	ds_read_b128 v[200:203], v211 offset:2048
	ds_read_b128 v[212:215], v211 offset:3072
	global_load_lds_dwordx4 v[216:217], off
	v_lshl_add_u64 v[218:219], s[56:57], 0, v[182:183]
	s_add_i32 m0, s63, 0x2000
	s_nop 0
	global_load_lds_dwordx4 v[218:219], off
	s_barrier
	s_waitcnt lgkmcnt(0)
	s_setprio 1
	s_waitcnt lgkmcnt(0)
	v_mfma_f32_16x16x32_bf16 v[116:119], v[192:195], v[144:147], 0
	v_mfma_f32_16x16x32_bf16 v[112:115], v[200:203], v[144:147], 0
	v_mfma_f32_16x16x32_bf16 v[100:103], v[192:195], v[152:155], 0
	v_mfma_f32_16x16x32_bf16 v[96:99], v[200:203], v[152:155], 0
	v_mfma_f32_16x16x32_bf16 v[84:87], v[192:195], v[160:163], 0
	v_mfma_f32_16x16x32_bf16 v[80:83], v[200:203], v[160:163], 0
	v_mfma_f32_16x16x32_bf16 v[68:71], v[192:195], v[168:171], 0
	v_mfma_f32_16x16x32_bf16 v[64:67], v[200:203], v[168:171], 0
	v_mfma_f32_16x16x32_bf16 v[116:119], v[196:199], v[148:151], v[116:119]
	v_mfma_f32_16x16x32_bf16 v[112:115], v[212:215], v[148:151], v[112:115]
	v_mfma_f32_16x16x32_bf16 v[100:103], v[196:199], v[156:159], v[100:103]
	v_mfma_f32_16x16x32_bf16 v[96:99], v[212:215], v[156:159], v[96:99]
	v_mfma_f32_16x16x32_bf16 v[84:87], v[196:199], v[164:167], v[84:87]
	v_mfma_f32_16x16x32_bf16 v[80:83], v[212:215], v[164:167], v[80:83]
	v_mfma_f32_16x16x32_bf16 v[68:71], v[196:199], v[172:175], v[68:71]
	v_mfma_f32_16x16x32_bf16 v[64:67], v[212:215], v[172:175], v[64:67]
	s_setprio 0
	s_mov_b32 m0, s21
	v_lshl_add_u64 v[220:221], s[58:59], 0, v[176:177]
	s_barrier
	ds_read_b128 v[144:147], v210 offset:16384
	ds_read_b128 v[148:151], v210 offset:17408
	ds_read_b128 v[152:155], v210 offset:18432
	ds_read_b128 v[156:159], v210 offset:19456
	ds_read_b128 v[160:163], v210 offset:20480
	ds_read_b128 v[164:167], v210 offset:21504
	ds_read_b128 v[168:171], v210 offset:22528
	ds_read_b128 v[172:175], v210 offset:23552
	global_load_lds_dwordx4 v[220:221], off
	v_lshl_add_u64 v[222:223], s[58:59], 0, v[180:181]
	s_mov_b32 m0, s33
	s_nop 0
	global_load_lds_dwordx4 v[222:223], off
	s_barrier
	s_waitcnt lgkmcnt(0)
	s_setprio 1
	s_waitcnt lgkmcnt(0)
	v_mfma_f32_16x16x32_bf16 v[60:63], v[128:131], v[144:147], 0
	v_mfma_f32_16x16x32_bf16 v[56:59], v[136:139], v[144:147], 0
	v_mfma_f32_16x16x32_bf16 v[44:47], v[128:131], v[152:155], 0
	v_mfma_f32_16x16x32_bf16 v[40:43], v[136:139], v[152:155], 0
	v_mfma_f32_16x16x32_bf16 v[28:31], v[128:131], v[160:163], 0
	v_mfma_f32_16x16x32_bf16 v[24:27], v[136:139], v[160:163], 0
	v_mfma_f32_16x16x32_bf16 v[12:15], v[128:131], v[168:171], 0
	v_mfma_f32_16x16x32_bf16 v[8:11], v[136:139], v[168:171], 0
	v_mfma_f32_16x16x32_bf16 v[60:63], v[132:135], v[148:151], v[60:63]
	v_mfma_f32_16x16x32_bf16 v[56:59], v[140:143], v[148:151], v[56:59]
	v_mfma_f32_16x16x32_bf16 v[44:47], v[132:135], v[156:159], v[44:47]
	v_mfma_f32_16x16x32_bf16 v[40:43], v[140:143], v[156:159], v[40:43]
	v_mfma_f32_16x16x32_bf16 v[28:31], v[132:135], v[164:167], v[28:31]
	v_mfma_f32_16x16x32_bf16 v[24:27], v[140:143], v[164:167], v[24:27]
	v_mfma_f32_16x16x32_bf16 v[12:15], v[132:135], v[172:175], v[12:15]
	v_mfma_f32_16x16x32_bf16 v[8:11], v[140:143], v[172:175], v[8:11]
	s_setprio 0
	s_barrier
	s_add_u32 s64, s56, 0x40000
	s_addc_u32 s65, s57, 0
	s_add_i32 s63, s49, s20
	v_lshl_add_u64 v[128:129], s[64:65], 0, v[178:179]
	s_mov_b32 m0, s63
	s_nop 0
	global_load_lds_dwordx4 v[128:129], off
	v_lshl_add_u64 v[128:129], s[64:65], 0, v[182:183]
	s_add_i32 m0, s63, 0x2000
	s_nop 0
	global_load_lds_dwordx4 v[128:129], off
	s_waitcnt vmcnt(6)
	s_barrier
	s_setprio 1
	v_mfma_f32_16x16x32_bf16 v[52:55], v[192:195], v[144:147], 0
	v_mfma_f32_16x16x32_bf16 v[48:51], v[200:203], v[144:147], 0
	v_mfma_f32_16x16x32_bf16 v[36:39], v[192:195], v[152:155], 0
	v_mfma_f32_16x16x32_bf16 v[32:35], v[200:203], v[152:155], 0
	v_mfma_f32_16x16x32_bf16 v[20:23], v[192:195], v[160:163], 0
	v_mfma_f32_16x16x32_bf16 v[16:19], v[200:203], v[160:163], 0
	v_mfma_f32_16x16x32_bf16 v[4:7], v[192:195], v[168:171], 0
	v_mfma_f32_16x16x32_bf16 v[0:3], v[200:203], v[168:171], 0
	v_mfma_f32_16x16x32_bf16 v[52:55], v[196:199], v[148:151], v[52:55]
	v_mfma_f32_16x16x32_bf16 v[48:51], v[212:215], v[148:151], v[48:51]
	v_mfma_f32_16x16x32_bf16 v[36:39], v[196:199], v[156:159], v[36:39]
	v_mfma_f32_16x16x32_bf16 v[32:35], v[212:215], v[156:159], v[32:35]
	v_mfma_f32_16x16x32_bf16 v[20:23], v[196:199], v[164:167], v[20:23]
	v_mfma_f32_16x16x32_bf16 v[16:19], v[212:215], v[164:167], v[16:19]
	v_mfma_f32_16x16x32_bf16 v[4:7], v[196:199], v[172:175], v[4:7]
	v_mfma_f32_16x16x32_bf16 v[0:3], v[212:215], v[172:175], v[0:3]
	s_setprio 0
	s_add_i32 s63, 0, 0x18000
	v_add_u32_e32 v140, s63, v207
	s_barrier
	ds_read_b128 v[128:131], v140
	ds_read_b128 v[132:135], v140 offset:1024
	ds_read_b128 v[136:139], v140 offset:2048
	ds_read_b128 v[140:143], v140 offset:3072
	s_add_u32 s58, s58, 0x40000
	s_addc_u32 s59, s59, 0
	s_mov_b32 m0, s34
	v_lshl_add_u64 v[192:193], s[58:59], 0, v[176:177]
	ds_read_b128 v[144:147], v210 offset:32768
	ds_read_b128 v[148:151], v210 offset:33792
	ds_read_b128 v[152:155], v210 offset:34816
	ds_read_b128 v[156:159], v210 offset:35840
	ds_read_b128 v[160:163], v210 offset:36864
	ds_read_b128 v[164:167], v210 offset:37888
	ds_read_b128 v[168:171], v210 offset:38912
	ds_read_b128 v[172:175], v210 offset:39936
	global_load_lds_dwordx4 v[192:193], off
	v_lshl_add_u64 v[192:193], s[58:59], 0, v[180:181]
	s_mov_b32 m0, s35
	s_nop 0
	global_load_lds_dwordx4 v[192:193], off
	s_waitcnt lgkmcnt(8)
	s_barrier
	s_waitcnt lgkmcnt(0)
	s_setprio 1
	s_waitcnt lgkmcnt(0)
	v_mfma_f32_16x16x32_bf16 v[124:127], v[128:131], v[144:147], v[124:127]
	v_mfma_f32_16x16x32_bf16 v[120:123], v[136:139], v[144:147], v[120:123]
	v_mfma_f32_16x16x32_bf16 v[108:111], v[128:131], v[152:155], v[108:111]
	v_mfma_f32_16x16x32_bf16 v[104:107], v[136:139], v[152:155], v[104:107]
	v_mfma_f32_16x16x32_bf16 v[92:95], v[128:131], v[160:163], v[92:95]
	v_mfma_f32_16x16x32_bf16 v[88:91], v[136:139], v[160:163], v[88:91]
	v_mfma_f32_16x16x32_bf16 v[76:79], v[128:131], v[168:171], v[76:79]
	v_mfma_f32_16x16x32_bf16 v[72:75], v[136:139], v[168:171], v[72:75]
	v_mfma_f32_16x16x32_bf16 v[124:127], v[132:135], v[148:151], v[124:127]
	v_mfma_f32_16x16x32_bf16 v[120:123], v[140:143], v[148:151], v[120:123]
	v_mfma_f32_16x16x32_bf16 v[108:111], v[132:135], v[156:159], v[108:111]
	v_mfma_f32_16x16x32_bf16 v[104:107], v[140:143], v[156:159], v[104:107]
	v_mfma_f32_16x16x32_bf16 v[92:95], v[132:135], v[164:167], v[92:95]
	v_mfma_f32_16x16x32_bf16 v[88:91], v[140:143], v[164:167], v[88:91]
	v_mfma_f32_16x16x32_bf16 v[76:79], v[132:135], v[172:175], v[76:79]
	v_mfma_f32_16x16x32_bf16 v[72:75], v[140:143], v[172:175], v[72:75]
	s_setprio 0
	s_barrier
	s_add_i32 s58, 0, 0x1c000
	s_add_i32 s59, s63, s20
	v_add_u32_e32 v212, s58, v207
	v_lshl_add_u64 v[216:217], v[216:217], 0, s[24:25]
	s_mov_b32 m0, s59
	ds_read_b128 v[192:195], v212
	ds_read_b128 v[196:199], v212 offset:1024
	ds_read_b128 v[200:203], v212 offset:2048
	ds_read_b128 v[212:215], v212 offset:3072
	global_load_lds_dwordx4 v[216:217], off
	v_lshl_add_u64 v[216:217], v[218:219], 0, s[24:25]
	s_add_i32 m0, s59, 0x2000
	s_nop 0
	global_load_lds_dwordx4 v[216:217], off
	s_barrier
	s_waitcnt lgkmcnt(0)
	s_setprio 1
	s_waitcnt lgkmcnt(0)
	v_mfma_f32_16x16x32_bf16 v[116:119], v[192:195], v[144:147], v[116:119]
	v_mfma_f32_16x16x32_bf16 v[112:115], v[200:203], v[144:147], v[112:115]
	v_mfma_f32_16x16x32_bf16 v[100:103], v[192:195], v[152:155], v[100:103]
	v_mfma_f32_16x16x32_bf16 v[96:99], v[200:203], v[152:155], v[96:99]
	v_mfma_f32_16x16x32_bf16 v[84:87], v[192:195], v[160:163], v[84:87]
	v_mfma_f32_16x16x32_bf16 v[80:83], v[200:203], v[160:163], v[80:83]
	v_mfma_f32_16x16x32_bf16 v[68:71], v[192:195], v[168:171], v[68:71]
	v_mfma_f32_16x16x32_bf16 v[64:67], v[200:203], v[168:171], v[64:67]
	v_mfma_f32_16x16x32_bf16 v[116:119], v[196:199], v[148:151], v[116:119]
	v_mfma_f32_16x16x32_bf16 v[112:115], v[212:215], v[148:151], v[112:115]
	v_mfma_f32_16x16x32_bf16 v[100:103], v[196:199], v[156:159], v[100:103]
	v_mfma_f32_16x16x32_bf16 v[96:99], v[212:215], v[156:159], v[96:99]
	v_mfma_f32_16x16x32_bf16 v[84:87], v[196:199], v[164:167], v[84:87]
	v_mfma_f32_16x16x32_bf16 v[80:83], v[212:215], v[164:167], v[80:83]
	v_mfma_f32_16x16x32_bf16 v[68:71], v[196:199], v[172:175], v[68:71]
	v_mfma_f32_16x16x32_bf16 v[64:67], v[212:215], v[172:175], v[64:67]
	s_setprio 0
	s_mov_b32 m0, s43
	v_lshl_add_u64 v[216:217], v[220:221], 0, s[24:25]
	s_barrier
	ds_read_b128 v[144:147], v210 offset:49152
	ds_read_b128 v[148:151], v210 offset:50176
	ds_read_b128 v[152:155], v210 offset:51200
	ds_read_b128 v[156:159], v210 offset:52224
	ds_read_b128 v[160:163], v210 offset:53248
	ds_read_b128 v[164:167], v210 offset:54272
	ds_read_b128 v[168:171], v210 offset:55296
	ds_read_b128 v[172:175], v210 offset:56320
	global_load_lds_dwordx4 v[216:217], off
	v_lshl_add_u64 v[216:217], v[222:223], 0, s[24:25]
	s_mov_b32 m0, s44
	s_nop 0
	global_load_lds_dwordx4 v[216:217], off
	s_barrier
	s_waitcnt lgkmcnt(0)
	s_setprio 1
	s_waitcnt lgkmcnt(0)
	v_mfma_f32_16x16x32_bf16 v[60:63], v[128:131], v[144:147], v[60:63]
	v_mfma_f32_16x16x32_bf16 v[56:59], v[136:139], v[144:147], v[56:59]
	v_mfma_f32_16x16x32_bf16 v[44:47], v[128:131], v[152:155], v[44:47]
	v_mfma_f32_16x16x32_bf16 v[40:43], v[136:139], v[152:155], v[40:43]
	v_mfma_f32_16x16x32_bf16 v[28:31], v[128:131], v[160:163], v[28:31]
	v_mfma_f32_16x16x32_bf16 v[24:27], v[136:139], v[160:163], v[24:27]
	v_mfma_f32_16x16x32_bf16 v[12:15], v[128:131], v[168:171], v[12:15]
	v_mfma_f32_16x16x32_bf16 v[8:11], v[136:139], v[168:171], v[8:11]
	v_mfma_f32_16x16x32_bf16 v[60:63], v[132:135], v[148:151], v[60:63]
	v_mfma_f32_16x16x32_bf16 v[56:59], v[140:143], v[148:151], v[56:59]
	v_mfma_f32_16x16x32_bf16 v[44:47], v[132:135], v[156:159], v[44:47]
	v_mfma_f32_16x16x32_bf16 v[40:43], v[140:143], v[156:159], v[40:43]
	v_mfma_f32_16x16x32_bf16 v[28:31], v[132:135], v[164:167], v[28:31]
	v_mfma_f32_16x16x32_bf16 v[24:27], v[140:143], v[164:167], v[24:27]
	v_mfma_f32_16x16x32_bf16 v[12:15], v[132:135], v[172:175], v[12:15]
	v_mfma_f32_16x16x32_bf16 v[8:11], v[140:143], v[172:175], v[8:11]
	s_setprio 0
	s_barrier
	s_add_u32 s56, s56, 0x40080
	s_addc_u32 s57, s57, 0
	s_add_i32 s58, s58, s20
	v_lshl_add_u64 v[128:129], s[56:57], 0, v[178:179]
	s_mov_b32 m0, s58
	s_nop 0
	global_load_lds_dwordx4 v[128:129], off
	v_lshl_add_u64 v[128:129], s[56:57], 0, v[182:183]
	s_add_i32 m0, s58, 0x2000
	s_nop 0
	global_load_lds_dwordx4 v[128:129], off
	s_waitcnt vmcnt(6)
	s_barrier
	s_setprio 1
	v_mfma_f32_16x16x32_bf16 v[52:55], v[192:195], v[144:147], v[52:55]
	v_mfma_f32_16x16x32_bf16 v[48:51], v[200:203], v[144:147], v[48:51]
	v_mfma_f32_16x16x32_bf16 v[36:39], v[192:195], v[152:155], v[36:39]
	v_mfma_f32_16x16x32_bf16 v[32:35], v[200:203], v[152:155], v[32:35]
	v_mfma_f32_16x16x32_bf16 v[20:23], v[192:195], v[160:163], v[20:23]
	v_mfma_f32_16x16x32_bf16 v[16:19], v[200:203], v[160:163], v[16:19]
	v_mfma_f32_16x16x32_bf16 v[4:7], v[192:195], v[168:171], v[4:7]
	v_mfma_f32_16x16x32_bf16 v[0:3], v[200:203], v[168:171], v[0:3]
	v_mfma_f32_16x16x32_bf16 v[52:55], v[196:199], v[148:151], v[52:55]
	v_mfma_f32_16x16x32_bf16 v[48:51], v[212:215], v[148:151], v[48:51]
	v_mfma_f32_16x16x32_bf16 v[36:39], v[196:199], v[156:159], v[36:39]
	v_mfma_f32_16x16x32_bf16 v[32:35], v[212:215], v[156:159], v[32:35]
	v_mfma_f32_16x16x32_bf16 v[20:23], v[196:199], v[164:167], v[20:23]
	v_mfma_f32_16x16x32_bf16 v[16:19], v[212:215], v[164:167], v[16:19]
	v_mfma_f32_16x16x32_bf16 v[4:7], v[196:199], v[172:175], v[4:7]
	v_mfma_f32_16x16x32_bf16 v[0:3], v[212:215], v[172:175], v[0:3]
	s_setprio 0
	s_add_i32 s62, s62, 2
	s_add_u32 s54, s54, 0x100
	s_addc_u32 s55, s55, 0
	s_add_u32 s60, s60, 0x100
	s_addc_u32 s61, s61, 0
	s_cmp_gt_u32 s62, 13
	s_barrier

.LBB0_986:
	s_ashr_i32 s51, s50, 31
	v_cmp_lt_i64_e32 vcc, s[52:53], v[140:141]
	s_lshl_b64 s[52:53], s[50:51], 19
	s_add_u32 s52, s2, s52
	s_addc_u32 s53, s20, s53
	s_and_b64 s[54:55], vcc, exec
	s_cselect_b32 s11, s53, s13
	s_cselect_b32 s51, s52, s12
	s_ashr_i32 s39, s38, 31
	s_lshl_b64 s[54:55], s[38:39], 19
	s_add_u32 s54, s21, s54
	s_addc_u32 s55, s33, s55
	s_and_b64 s[58:59], vcc, exec
	s_cselect_b32 s39, s55, s57
	s_cselect_b32 s68, s54, s56
	s_add_u32 s12, s12, 0x40080
	s_addc_u32 s13, s13, 0
	s_add_u32 s69, s56, 0x100

	s_addc_u32 s70, s57, 0
	s_mov_b32 s71, -2


	ds_read_b128 v[164:167], v155
	ds_read_b128 v[168:171], v155 offset:1024
	ds_read_b128 v[172:175], v155 offset:2048
	ds_read_b128 v[176:179], v155 offset:3072
	s_add_u32 s56, s12, 0xfffc0080
	s_addc_u32 s57, s13, -1
	s_cmp_eq_u32 s71, 12
	s_cselect_b32 s59, s11, s57
	s_cselect_b32 s58, s51, s56
	s_cselect_b32 s57, s39, s70
	s_cselect_b32 s56, s68, s69
	v_lshl_add_u64 v[146:147], s[12:13], 0, v[136:137]
	s_add_i32 m0, s35, 0xc000
	ds_read_b128 v[180:183], v159
	ds_read_b128 v[184:187], v159 offset:1024
	ds_read_b128 v[188:191], v159 offset:2048
	ds_read_b128 v[192:195], v159 offset:3072
	ds_read_b128 v[196:199], v159 offset:4096
	ds_read_b128 v[200:203], v159 offset:5120
	ds_read_b128 v[206:209], v159 offset:6144
	ds_read_b128 v[210:213], v159 offset:7168
	global_load_lds_dwordx4 v[146:147], off
	v_lshl_add_u64 v[146:147], s[12:13], 0, v[138:139]
	s_add_i32 m0, s35, 0xe000
	s_nop 0
	global_load_lds_dwordx4 v[146:147], off
	s_waitcnt lgkmcnt(8)
	s_barrier
	s_waitcnt lgkmcnt(0)
	s_setprio 1
	s_waitcnt lgkmcnt(0)
	v_mfma_f32_16x16x32_bf16 v[124:127], v[164:167], v[180:183], 0
	v_mfma_f32_16x16x32_bf16 v[120:123], v[172:175], v[180:183], 0
	v_mfma_f32_16x16x32_bf16 v[108:111], v[164:167], v[188:191], 0
	v_mfma_f32_16x16x32_bf16 v[104:107], v[172:175], v[188:191], 0
	v_mfma_f32_16x16x32_bf16 v[92:95], v[164:167], v[196:199], 0
	v_mfma_f32_16x16x32_bf16 v[88:91], v[172:175], v[196:199], 0
	v_mfma_f32_16x16x32_bf16 v[76:79], v[164:167], v[206:209], 0
	v_mfma_f32_16x16x32_bf16 v[72:75], v[172:175], v[206:209], 0
	v_mfma_f32_16x16x32_bf16 v[124:127], v[168:171], v[184:187], v[124:127]
	v_mfma_f32_16x16x32_bf16 v[120:123], v[176:179], v[184:187], v[120:123]
	v_mfma_f32_16x16x32_bf16 v[108:111], v[168:171], v[192:195], v[108:111]
	v_mfma_f32_16x16x32_bf16 v[104:107], v[176:179], v[192:195], v[104:107]
	v_mfma_f32_16x16x32_bf16 v[92:95], v[168:171], v[200:203], v[92:95]
	v_mfma_f32_16x16x32_bf16 v[88:91], v[176:179], v[200:203], v[88:91]
	v_mfma_f32_16x16x32_bf16 v[76:79], v[168:171], v[210:213], v[76:79]
	v_mfma_f32_16x16x32_bf16 v[72:75], v[176:179], v[210:213], v[72:75]
	s_setprio 0
	s_barrier
	s_add_i32 s72, s60, s34
	v_lshl_add_u64 v[146:147], s[56:57], 0, v[130:131]
	s_mov_b32 m0, s72
	ds_read_b128 v[214:217], v162
	ds_read_b128 v[218:221], v162 offset:1024
	ds_read_b128 v[222:225], v162 offset:2048
	ds_read_b128 v[226:229], v162 offset:3072
	global_load_lds_dwordx4 v[146:147], off
	v_lshl_add_u64 v[152:153], s[56:57], 0, v[134:135]
	s_add_i32 m0, s72, 0x2000
	s_nop 0
	global_load_lds_dwordx4 v[152:153], off
	s_barrier
	s_waitcnt lgkmcnt(0)
	s_setprio 1
	s_waitcnt lgkmcnt(0)
	v_mfma_f32_16x16x32_bf16 v[116:119], v[214:217], v[180:183], 0
	v_mfma_f32_16x16x32_bf16 v[112:115], v[222:225], v[180:183], 0
	v_mfma_f32_16x16x32_bf16 v[100:103], v[214:217], v[188:191], 0
	v_mfma_f32_16x16x32_bf16 v[96:99], v[222:225], v[188:191], 0
	v_mfma_f32_16x16x32_bf16 v[84:87], v[214:217], v[196:199], 0
	v_mfma_f32_16x16x32_bf16 v[80:83], v[222:225], v[196:199], 0
	v_mfma_f32_16x16x32_bf16 v[68:71], v[214:217], v[206:209], 0
	v_mfma_f32_16x16x32_bf16 v[64:67], v[222:225], v[206:209], 0
	v_mfma_f32_16x16x32_bf16 v[116:119], v[218:221], v[184:187], v[116:119]
	v_mfma_f32_16x16x32_bf16 v[112:115], v[226:229], v[184:187], v[112:115]
	v_mfma_f32_16x16x32_bf16 v[100:103], v[218:221], v[192:195], v[100:103]
	v_mfma_f32_16x16x32_bf16 v[96:99], v[226:229], v[192:195], v[96:99]
	v_mfma_f32_16x16x32_bf16 v[84:87], v[218:221], v[200:203], v[84:87]
	v_mfma_f32_16x16x32_bf16 v[80:83], v[226:229], v[200:203], v[80:83]
	v_mfma_f32_16x16x32_bf16 v[68:71], v[218:221], v[210:213], v[68:71]
	v_mfma_f32_16x16x32_bf16 v[64:67], v[226:229], v[210:213], v[64:67]
	s_setprio 0
	s_mov_b32 m0, s35
	v_lshl_add_u64 v[156:157], s[58:59], 0, v[128:129]
	s_barrier
	ds_read_b128 v[180:183], v159 offset:16384
	ds_read_b128 v[184:187], v159 offset:17408
	ds_read_b128 v[188:191], v159 offset:18432
	ds_read_b128 v[192:195], v159 offset:19456
	ds_read_b128 v[196:199], v159 offset:20480
	ds_read_b128 v[200:203], v159 offset:21504
	ds_read_b128 v[206:209], v159 offset:22528
	ds_read_b128 v[210:213], v159 offset:23552
	global_load_lds_dwordx4 v[156:157], off
	v_lshl_add_u64 v[160:161], s[58:59], 0, v[132:133]
	s_mov_b32 m0, s42
	s_nop 0
	global_load_lds_dwordx4 v[160:161], off
	s_barrier
	s_waitcnt lgkmcnt(0)
	s_setprio 1
	s_waitcnt lgkmcnt(0)
	v_mfma_f32_16x16x32_bf16 v[60:63], v[164:167], v[180:183], 0
	v_mfma_f32_16x16x32_bf16 v[56:59], v[172:175], v[180:183], 0
	v_mfma_f32_16x16x32_bf16 v[44:47], v[164:167], v[188:191], 0
	v_mfma_f32_16x16x32_bf16 v[40:43], v[172:175], v[188:191], 0
	v_mfma_f32_16x16x32_bf16 v[28:31], v[164:167], v[196:199], 0
	v_mfma_f32_16x16x32_bf16 v[24:27], v[172:175], v[196:199], 0
	v_mfma_f32_16x16x32_bf16 v[12:15], v[164:167], v[206:209], 0
	v_mfma_f32_16x16x32_bf16 v[8:11], v[172:175], v[206:209], 0
	v_mfma_f32_16x16x32_bf16 v[60:63], v[168:171], v[184:187], v[60:63]
	v_mfma_f32_16x16x32_bf16 v[56:59], v[176:179], v[184:187], v[56:59]
	v_mfma_f32_16x16x32_bf16 v[44:47], v[168:171], v[192:195], v[44:47]
	v_mfma_f32_16x16x32_bf16 v[40:43], v[176:179], v[192:195], v[40:43]
	v_mfma_f32_16x16x32_bf16 v[28:31], v[168:171], v[200:203], v[28:31]
	v_mfma_f32_16x16x32_bf16 v[24:27], v[176:179], v[200:203], v[24:27]
	v_mfma_f32_16x16x32_bf16 v[12:15], v[168:171], v[210:213], v[12:15]
	v_mfma_f32_16x16x32_bf16 v[8:11], v[176:179], v[210:213], v[8:11]
	s_setprio 0
	s_barrier
	s_add_u32 s72, s56, 0x40000
	s_addc_u32 s73, s57, 0
	s_add_i32 s74, s61, s34
	v_lshl_add_u64 v[164:165], s[72:73], 0, v[130:131]
	s_mov_b32 m0, s74
	s_nop 0
	global_load_lds_dwordx4 v[164:165], off
	v_lshl_add_u64 v[164:165], s[72:73], 0, v[134:135]
	s_add_i32 m0, s74, 0x2000
	s_nop 0
	global_load_lds_dwordx4 v[164:165], off
	s_waitcnt vmcnt(6)
	s_barrier
	s_setprio 1
	v_mfma_f32_16x16x32_bf16 v[52:55], v[214:217], v[180:183], 0
	v_mfma_f32_16x16x32_bf16 v[48:51], v[222:225], v[180:183], 0
	v_mfma_f32_16x16x32_bf16 v[36:39], v[214:217], v[188:191], 0
	v_mfma_f32_16x16x32_bf16 v[32:35], v[222:225], v[188:191], 0
	v_mfma_f32_16x16x32_bf16 v[20:23], v[214:217], v[196:199], 0
	v_mfma_f32_16x16x32_bf16 v[16:19], v[222:225], v[196:199], 0
	v_mfma_f32_16x16x32_bf16 v[4:7], v[214:217], v[206:209], 0
	v_mfma_f32_16x16x32_bf16 v[0:3], v[222:225], v[206:209], 0
	v_mfma_f32_16x16x32_bf16 v[52:55], v[218:221], v[184:187], v[52:55]
	v_mfma_f32_16x16x32_bf16 v[48:51], v[226:229], v[184:187], v[48:51]
	v_mfma_f32_16x16x32_bf16 v[36:39], v[218:221], v[192:195], v[36:39]
	v_mfma_f32_16x16x32_bf16 v[32:35], v[226:229], v[192:195], v[32:35]
	v_mfma_f32_16x16x32_bf16 v[20:23], v[218:221], v[200:203], v[20:23]
	v_mfma_f32_16x16x32_bf16 v[16:19], v[226:229], v[200:203], v[16:19]
	v_mfma_f32_16x16x32_bf16 v[4:7], v[218:221], v[210:213], v[4:7]
	v_mfma_f32_16x16x32_bf16 v[0:3], v[226:229], v[210:213], v[0:3]
	s_setprio 0
	s_add_i32 s72, 0, 0x18000
	v_add_u32_e32 v144, s72, v149
	s_barrier
	ds_read_b128 v[164:167], v144
	ds_read_b128 v[168:171], v144 offset:1024
	ds_read_b128 v[172:175], v144 offset:2048
	ds_read_b128 v[176:179], v144 offset:3072
	s_add_u32 s58, s58, 0x40000
	s_addc_u32 s59, s59, 0
	s_mov_b32 m0, s43
	v_lshl_add_u64 v[214:215], s[58:59], 0, v[128:129]
	ds_read_b128 v[180:183], v159 offset:32768
	ds_read_b128 v[184:187], v159 offset:33792
	ds_read_b128 v[188:191], v159 offset:34816
	ds_read_b128 v[192:195], v159 offset:35840
	ds_read_b128 v[196:199], v159 offset:36864
	ds_read_b128 v[200:203], v159 offset:37888
	ds_read_b128 v[206:209], v159 offset:38912
	ds_read_b128 v[210:213], v159 offset:39936
	global_load_lds_dwordx4 v[214:215], off
	v_lshl_add_u64 v[214:215], s[58:59], 0, v[132:133]
	s_mov_b32 m0, s44
	s_nop 0
	global_load_lds_dwordx4 v[214:215], off
	s_waitcnt lgkmcnt(8)
	s_barrier
	s_waitcnt lgkmcnt(0)
	s_setprio 1
	s_waitcnt lgkmcnt(0)
	v_mfma_f32_16x16x32_bf16 v[124:127], v[164:167], v[180:183], v[124:127]
	v_mfma_f32_16x16x32_bf16 v[120:123], v[172:175], v[180:183], v[120:123]
	v_mfma_f32_16x16x32_bf16 v[108:111], v[164:167], v[188:191], v[108:111]
	v_mfma_f32_16x16x32_bf16 v[104:107], v[172:175], v[188:191], v[104:107]
	v_mfma_f32_16x16x32_bf16 v[92:95], v[164:167], v[196:199], v[92:95]
	v_mfma_f32_16x16x32_bf16 v[88:91], v[172:175], v[196:199], v[88:91]
	v_mfma_f32_16x16x32_bf16 v[76:79], v[164:167], v[206:209], v[76:79]
	v_mfma_f32_16x16x32_bf16 v[72:75], v[172:175], v[206:209], v[72:75]
	v_mfma_f32_16x16x32_bf16 v[124:127], v[168:171], v[184:187], v[124:127]
	v_mfma_f32_16x16x32_bf16 v[120:123], v[176:179], v[184:187], v[120:123]
	v_mfma_f32_16x16x32_bf16 v[108:111], v[168:171], v[192:195], v[108:111]
	v_mfma_f32_16x16x32_bf16 v[104:107], v[176:179], v[192:195], v[104:107]
	v_mfma_f32_16x16x32_bf16 v[92:95], v[168:171], v[200:203], v[92:95]
	v_mfma_f32_16x16x32_bf16 v[88:91], v[176:179], v[200:203], v[88:91]
	v_mfma_f32_16x16x32_bf16 v[76:79], v[168:171], v[210:213], v[76:79]
	v_mfma_f32_16x16x32_bf16 v[72:75], v[176:179], v[210:213], v[72:75]
	s_setprio 0
	s_barrier
	s_add_i32 s58, 0, 0x1c000
	s_add_i32 s59, s72, s34
	v_add_u32_e32 v144, s58, v149
	v_lshl_add_u64 v[146:147], v[146:147], 0, s[24:25]
	s_mov_b32 m0, s59
	ds_read_b128 v[214:217], v144
	ds_read_b128 v[218:221], v144 offset:1024
	ds_read_b128 v[222:225], v144 offset:2048
	ds_read_b128 v[226:229], v144 offset:3072
	global_load_lds_dwordx4 v[146:147], off
	v_lshl_add_u64 v[146:147], v[152:153], 0, s[24:25]
	s_add_i32 m0, s59, 0x2000
	s_nop 0
	global_load_lds_dwordx4 v[146:147], off
	s_barrier
	s_waitcnt lgkmcnt(0)
	s_setprio 1
	s_waitcnt lgkmcnt(0)
	v_mfma_f32_16x16x32_bf16 v[116:119], v[214:217], v[180:183], v[116:119]
	v_mfma_f32_16x16x32_bf16 v[112:115], v[222:225], v[180:183], v[112:115]
	v_mfma_f32_16x16x32_bf16 v[100:103], v[214:217], v[188:191], v[100:103]
	v_mfma_f32_16x16x32_bf16 v[96:99], v[222:225], v[188:191], v[96:99]
	v_mfma_f32_16x16x32_bf16 v[84:87], v[214:217], v[196:199], v[84:87]
	v_mfma_f32_16x16x32_bf16 v[80:83], v[222:225], v[196:199], v[80:83]
	v_mfma_f32_16x16x32_bf16 v[68:71], v[214:217], v[206:209], v[68:71]
	v_mfma_f32_16x16x32_bf16 v[64:67], v[222:225], v[206:209], v[64:67]
	v_mfma_f32_16x16x32_bf16 v[116:119], v[218:221], v[184:187], v[116:119]
	v_mfma_f32_16x16x32_bf16 v[112:115], v[226:229], v[184:187], v[112:115]
	v_mfma_f32_16x16x32_bf16 v[100:103], v[218:221], v[192:195], v[100:103]
	v_mfma_f32_16x16x32_bf16 v[96:99], v[226:229], v[192:195], v[96:99]
	v_mfma_f32_16x16x32_bf16 v[84:87], v[218:221], v[200:203], v[84:87]
	v_mfma_f32_16x16x32_bf16 v[80:83], v[226:229], v[200:203], v[80:83]
	v_mfma_f32_16x16x32_bf16 v[68:71], v[218:221], v[210:213], v[68:71]
	v_mfma_f32_16x16x32_bf16 v[64:67], v[226:229], v[210:213], v[64:67]
	s_setprio 0
	s_mov_b32 m0, s46
	v_lshl_add_u64 v[146:147], v[156:157], 0, s[24:25]
	s_barrier
	ds_read_b128 v[180:183], v159 offset:49152
	ds_read_b128 v[184:187], v159 offset:50176
	ds_read_b128 v[188:191], v159 offset:51200
	ds_read_b128 v[192:195], v159 offset:52224
	ds_read_b128 v[196:199], v159 offset:53248
	ds_read_b128 v[200:203], v159 offset:54272
	ds_read_b128 v[206:209], v159 offset:55296
	ds_read_b128 v[210:213], v159 offset:56320
	global_load_lds_dwordx4 v[146:147], off
	v_lshl_add_u64 v[146:147], v[160:161], 0, s[24:25]
	s_mov_b32 m0, s47
	s_nop 0
	global_load_lds_dwordx4 v[146:147], off
	s_barrier
	s_waitcnt lgkmcnt(0)
	s_setprio 1
	s_waitcnt lgkmcnt(0)
	v_mfma_f32_16x16x32_bf16 v[60:63], v[164:167], v[180:183], v[60:63]
	v_mfma_f32_16x16x32_bf16 v[56:59], v[172:175], v[180:183], v[56:59]
	v_mfma_f32_16x16x32_bf16 v[44:47], v[164:167], v[188:191], v[44:47]
	v_mfma_f32_16x16x32_bf16 v[40:43], v[172:175], v[188:191], v[40:43]
	v_mfma_f32_16x16x32_bf16 v[28:31], v[164:167], v[196:199], v[28:31]
	v_mfma_f32_16x16x32_bf16 v[24:27], v[172:175], v[196:199], v[24:27]
	v_mfma_f32_16x16x32_bf16 v[12:15], v[164:167], v[206:209], v[12:15]
	v_mfma_f32_16x16x32_bf16 v[8:11], v[172:175], v[206:209], v[8:11]
	v_mfma_f32_16x16x32_bf16 v[60:63], v[168:171], v[184:187], v[60:63]
	v_mfma_f32_16x16x32_bf16 v[56:59], v[176:179], v[184:187], v[56:59]
	v_mfma_f32_16x16x32_bf16 v[44:47], v[168:171], v[192:195], v[44:47]
	v_mfma_f32_16x16x32_bf16 v[40:43], v[176:179], v[192:195], v[40:43]
	v_mfma_f32_16x16x32_bf16 v[28:31], v[168:171], v[200:203], v[28:31]
	v_mfma_f32_16x16x32_bf16 v[24:27], v[176:179], v[200:203], v[24:27]
	v_mfma_f32_16x16x32_bf16 v[12:15], v[168:171], v[210:213], v[12:15]
	v_mfma_f32_16x16x32_bf16 v[8:11], v[176:179], v[210:213], v[8:11]
	s_setprio 0
	s_barrier
	s_add_u32 s56, s56, 0x40080
	s_addc_u32 s57, s57, 0
	s_add_i32 s58, s58, s34
	v_lshl_add_u64 v[146:147], s[56:57], 0, v[130:131]
	s_mov_b32 m0, s58
	s_nop 0
	global_load_lds_dwordx4 v[146:147], off
	v_lshl_add_u64 v[146:147], s[56:57], 0, v[134:135]
	s_add_i32 m0, s58, 0x2000
	s_nop 0
	global_load_lds_dwordx4 v[146:147], off
	s_waitcnt vmcnt(6)
	s_barrier
	s_setprio 1
	v_mfma_f32_16x16x32_bf16 v[52:55], v[214:217], v[180:183], v[52:55]
	v_mfma_f32_16x16x32_bf16 v[48:51], v[222:225], v[180:183], v[48:51]
	v_mfma_f32_16x16x32_bf16 v[36:39], v[214:217], v[188:191], v[36:39]
	v_mfma_f32_16x16x32_bf16 v[32:35], v[222:225], v[188:191], v[32:35]
	v_mfma_f32_16x16x32_bf16 v[20:23], v[214:217], v[196:199], v[20:23]
	v_mfma_f32_16x16x32_bf16 v[16:19], v[222:225], v[196:199], v[16:19]
	v_mfma_f32_16x16x32_bf16 v[4:7], v[214:217], v[206:209], v[4:7]
	v_mfma_f32_16x16x32_bf16 v[0:3], v[222:225], v[206:209], v[0:3]
	v_mfma_f32_16x16x32_bf16 v[52:55], v[218:221], v[184:187], v[52:55]
	v_mfma_f32_16x16x32_bf16 v[48:51], v[226:229], v[184:187], v[48:51]
	v_mfma_f32_16x16x32_bf16 v[36:39], v[218:221], v[192:195], v[36:39]
	v_mfma_f32_16x16x32_bf16 v[32:35], v[226:229], v[192:195], v[32:35]
	v_mfma_f32_16x16x32_bf16 v[20:23], v[218:221], v[200:203], v[20:23]
	v_mfma_f32_16x16x32_bf16 v[16:19], v[226:229], v[200:203], v[16:19]
	v_mfma_f32_16x16x32_bf16 v[4:7], v[218:221], v[210:213], v[4:7]
	v_mfma_f32_16x16x32_bf16 v[0:3], v[226:229], v[210:213], v[0:3]
	s_setprio 0
	s_add_i32 s71, s71, 2
	s_add_u32 s12, s12, 0x100
	s_addc_u32 s13, s13, 0
	s_add_u32 s69, s69, 0x100
	s_addc_u32 s70, s70, 0
	s_cmp_gt_u32 s71, 13
	s_barrier

.LBB0_1061:
	s_ashr_i32 s27, s26, 31
	v_cmp_lt_i64_e32 vcc, s[28:29], v[164:165]
	s_lshl_b64 s[28:29], s[26:27], 21
	s_add_u32 s28, s1, s28
	s_addc_u32 s29, s2, s29
	s_and_b64 s[30:31], vcc, exec
	s_cselect_b32 s27, s29, s51
	s_cselect_b32 s37, s28, s50
	s_ashr_i32 s25, s24, 31
	s_lshl_b64 s[30:31], s[24:25], 21
	s_add_u32 s30, s20, s30
	s_addc_u32 s31, s21, s31
	s_and_b64 s[54:55], vcc, exec
	s_cselect_b32 s25, s31, s53
	s_cselect_b32 s57, s30, s52
	s_add_u32 s50, s50, 0x100080
	s_addc_u32 s51, s51, 0
	s_add_u32 s58, s52, 0x100

	s_addc_u32 s59, s53, 0
	s_mov_b32 s60, -2
	s_waitcnt lgkmcnt(0)


	ds_read_b128 v[128:131], v189
	ds_read_b128 v[132:135], v189 offset:1024
	ds_read_b128 v[136:139], v189 offset:2048
	ds_read_b128 v[140:143], v189 offset:3072
	s_add_u32 s52, s50, 0xfff00080
	s_addc_u32 s53, s51, -1
	s_cmp_eq_u32 s60, 60
	s_cselect_b32 s55, s27, s53
	s_cselect_b32 s54, s37, s52
	s_cselect_b32 s53, s25, s59
	s_cselect_b32 s52, s57, s58
	v_lshl_add_u64 v[184:185], s[50:51], 0, v[160:161]
	s_add_i32 m0, s34, 0xc000
	ds_read_b128 v[144:147], v190
	ds_read_b128 v[148:151], v190 offset:1024
	ds_read_b128 v[168:171], v190 offset:2048
	ds_read_b128 v[172:175], v190 offset:3072
	ds_read_b128 v[176:179], v190 offset:4096
	ds_read_b128 v[180:183], v190 offset:5120
	ds_read_b128 v[192:195], v190 offset:6144
	ds_read_b128 v[196:199], v190 offset:7168
	global_load_lds_dwordx4 v[184:185], off
	v_lshl_add_u64 v[184:185], s[50:51], 0, v[162:163]
	s_add_i32 m0, s34, 0xe000
	s_nop 0
	global_load_lds_dwordx4 v[184:185], off
	s_waitcnt lgkmcnt(8)
	s_barrier
	s_waitcnt lgkmcnt(0)
	s_setprio 1
	s_waitcnt lgkmcnt(0)
	v_mfma_f32_16x16x32_bf16 v[124:127], v[128:131], v[144:147], 0
	v_mfma_f32_16x16x32_bf16 v[120:123], v[136:139], v[144:147], 0
	v_mfma_f32_16x16x32_bf16 v[108:111], v[128:131], v[168:171], 0
	v_mfma_f32_16x16x32_bf16 v[104:107], v[136:139], v[168:171], 0
	v_mfma_f32_16x16x32_bf16 v[92:95], v[128:131], v[176:179], 0
	v_mfma_f32_16x16x32_bf16 v[88:91], v[136:139], v[176:179], 0
	v_mfma_f32_16x16x32_bf16 v[76:79], v[128:131], v[192:195], 0
	v_mfma_f32_16x16x32_bf16 v[72:75], v[136:139], v[192:195], 0
	v_mfma_f32_16x16x32_bf16 v[124:127], v[132:135], v[148:151], v[124:127]
	v_mfma_f32_16x16x32_bf16 v[120:123], v[140:143], v[148:151], v[120:123]
	v_mfma_f32_16x16x32_bf16 v[108:111], v[132:135], v[172:175], v[108:111]
	v_mfma_f32_16x16x32_bf16 v[104:107], v[140:143], v[172:175], v[104:107]
	v_mfma_f32_16x16x32_bf16 v[92:95], v[132:135], v[180:183], v[92:95]
	v_mfma_f32_16x16x32_bf16 v[88:91], v[140:143], v[180:183], v[88:91]
	v_mfma_f32_16x16x32_bf16 v[76:79], v[132:135], v[196:199], v[76:79]
	v_mfma_f32_16x16x32_bf16 v[72:75], v[140:143], v[196:199], v[72:75]
	s_setprio 0
	s_barrier
	s_add_i32 s61, s49, s33
	v_lshl_add_u64 v[184:185], s[52:53], 0, v[154:155]
	s_mov_b32 m0, s61
	ds_read_b128 v[200:203], v191
	ds_read_b128 v[206:209], v191 offset:1024
	ds_read_b128 v[210:213], v191 offset:2048
	ds_read_b128 v[214:217], v191 offset:3072
	global_load_lds_dwordx4 v[184:185], off
	v_lshl_add_u64 v[218:219], s[52:53], 0, v[158:159]
	s_add_i32 m0, s61, 0x2000
	s_nop 0
	global_load_lds_dwordx4 v[218:219], off
	s_barrier
	s_waitcnt lgkmcnt(0)
	s_setprio 1
	s_waitcnt lgkmcnt(0)
	v_mfma_f32_16x16x32_bf16 v[116:119], v[200:203], v[144:147], 0
	v_mfma_f32_16x16x32_bf16 v[112:115], v[210:213], v[144:147], 0
	v_mfma_f32_16x16x32_bf16 v[100:103], v[200:203], v[168:171], 0
	v_mfma_f32_16x16x32_bf16 v[96:99], v[210:213], v[168:171], 0
	v_mfma_f32_16x16x32_bf16 v[84:87], v[200:203], v[176:179], 0
	v_mfma_f32_16x16x32_bf16 v[80:83], v[210:213], v[176:179], 0
	v_mfma_f32_16x16x32_bf16 v[68:71], v[200:203], v[192:195], 0
	v_mfma_f32_16x16x32_bf16 v[64:67], v[210:213], v[192:195], 0
	v_mfma_f32_16x16x32_bf16 v[116:119], v[206:209], v[148:151], v[116:119]
	v_mfma_f32_16x16x32_bf16 v[112:115], v[214:217], v[148:151], v[112:115]
	v_mfma_f32_16x16x32_bf16 v[100:103], v[206:209], v[172:175], v[100:103]
	v_mfma_f32_16x16x32_bf16 v[96:99], v[214:217], v[172:175], v[96:99]
	v_mfma_f32_16x16x32_bf16 v[84:87], v[206:209], v[180:183], v[84:87]
	v_mfma_f32_16x16x32_bf16 v[80:83], v[214:217], v[180:183], v[80:83]
	v_mfma_f32_16x16x32_bf16 v[68:71], v[206:209], v[196:199], v[68:71]
	v_mfma_f32_16x16x32_bf16 v[64:67], v[214:217], v[196:199], v[64:67]
	s_setprio 0
	s_mov_b32 m0, s34
	v_lshl_add_u64 v[220:221], s[54:55], 0, v[152:153]
	s_barrier
	ds_read_b128 v[144:147], v190 offset:16384
	ds_read_b128 v[148:151], v190 offset:17408
	ds_read_b128 v[168:171], v190 offset:18432
	ds_read_b128 v[172:175], v190 offset:19456
	ds_read_b128 v[176:179], v190 offset:20480
	ds_read_b128 v[180:183], v190 offset:21504
	ds_read_b128 v[192:195], v190 offset:22528
	ds_read_b128 v[196:199], v190 offset:23552
	global_load_lds_dwordx4 v[220:221], off
	v_lshl_add_u64 v[222:223], s[54:55], 0, v[156:157]
	s_mov_b32 m0, s35
	s_nop 0
	global_load_lds_dwordx4 v[222:223], off
	s_barrier
	s_waitcnt lgkmcnt(0)
	s_setprio 1
	s_waitcnt lgkmcnt(0)
	v_mfma_f32_16x16x32_bf16 v[60:63], v[128:131], v[144:147], 0
	v_mfma_f32_16x16x32_bf16 v[56:59], v[136:139], v[144:147], 0
	v_mfma_f32_16x16x32_bf16 v[44:47], v[128:131], v[168:171], 0
	v_mfma_f32_16x16x32_bf16 v[40:43], v[136:139], v[168:171], 0
	v_mfma_f32_16x16x32_bf16 v[28:31], v[128:131], v[176:179], 0
	v_mfma_f32_16x16x32_bf16 v[24:27], v[136:139], v[176:179], 0
	v_mfma_f32_16x16x32_bf16 v[12:15], v[128:131], v[192:195], 0
	v_mfma_f32_16x16x32_bf16 v[8:11], v[136:139], v[192:195], 0
	v_mfma_f32_16x16x32_bf16 v[60:63], v[132:135], v[148:151], v[60:63]
	v_mfma_f32_16x16x32_bf16 v[56:59], v[140:143], v[148:151], v[56:59]
	v_mfma_f32_16x16x32_bf16 v[44:47], v[132:135], v[172:175], v[44:47]
	v_mfma_f32_16x16x32_bf16 v[40:43], v[140:143], v[172:175], v[40:43]
	v_mfma_f32_16x16x32_bf16 v[28:31], v[132:135], v[180:183], v[28:31]
	v_mfma_f32_16x16x32_bf16 v[24:27], v[140:143], v[180:183], v[24:27]
	v_mfma_f32_16x16x32_bf16 v[12:15], v[132:135], v[196:199], v[12:15]
	v_mfma_f32_16x16x32_bf16 v[8:11], v[140:143], v[196:199], v[8:11]
	s_setprio 0
	s_barrier
	s_add_u32 s62, s52, 0x100000
	s_addc_u32 s63, s53, 0
	s_add_i32 s61, s56, s33
	v_lshl_add_u64 v[128:129], s[62:63], 0, v[154:155]
	s_mov_b32 m0, s61
	s_nop 0
	global_load_lds_dwordx4 v[128:129], off
	v_lshl_add_u64 v[128:129], s[62:63], 0, v[158:159]
	s_add_i32 m0, s61, 0x2000
	s_nop 0
	global_load_lds_dwordx4 v[128:129], off
	s_waitcnt vmcnt(6)
	s_barrier
	s_setprio 1
	v_mfma_f32_16x16x32_bf16 v[52:55], v[200:203], v[144:147], 0
	v_mfma_f32_16x16x32_bf16 v[48:51], v[210:213], v[144:147], 0
	v_mfma_f32_16x16x32_bf16 v[36:39], v[200:203], v[168:171], 0
	v_mfma_f32_16x16x32_bf16 v[32:35], v[210:213], v[168:171], 0
	v_mfma_f32_16x16x32_bf16 v[20:23], v[200:203], v[176:179], 0
	v_mfma_f32_16x16x32_bf16 v[16:19], v[210:213], v[176:179], 0
	v_mfma_f32_16x16x32_bf16 v[4:7], v[200:203], v[192:195], 0
	v_mfma_f32_16x16x32_bf16 v[0:3], v[210:213], v[192:195], 0
	v_mfma_f32_16x16x32_bf16 v[52:55], v[206:209], v[148:151], v[52:55]
	v_mfma_f32_16x16x32_bf16 v[48:51], v[214:217], v[148:151], v[48:51]
	v_mfma_f32_16x16x32_bf16 v[36:39], v[206:209], v[172:175], v[36:39]
	v_mfma_f32_16x16x32_bf16 v[32:35], v[214:217], v[172:175], v[32:35]
	v_mfma_f32_16x16x32_bf16 v[20:23], v[206:209], v[180:183], v[20:23]
	v_mfma_f32_16x16x32_bf16 v[16:19], v[214:217], v[180:183], v[16:19]
	v_mfma_f32_16x16x32_bf16 v[4:7], v[206:209], v[196:199], v[4:7]
	v_mfma_f32_16x16x32_bf16 v[0:3], v[214:217], v[196:199], v[0:3]
	s_setprio 0
	s_add_i32 s61, 0, 0x18000
	v_add_u32_e32 v140, s61, v187
	s_barrier
	ds_read_b128 v[128:131], v140
	ds_read_b128 v[132:135], v140 offset:1024
	ds_read_b128 v[136:139], v140 offset:2048
	ds_read_b128 v[140:143], v140 offset:3072
	s_add_u32 s54, s54, 0x100000
	s_addc_u32 s55, s55, 0
	s_mov_b32 m0, s39
	v_lshl_add_u64 v[200:201], s[54:55], 0, v[152:153]
	ds_read_b128 v[144:147], v190 offset:32768
	ds_read_b128 v[148:151], v190 offset:33792
	ds_read_b128 v[168:171], v190 offset:34816
	ds_read_b128 v[172:175], v190 offset:35840
	ds_read_b128 v[176:179], v190 offset:36864
	ds_read_b128 v[180:183], v190 offset:37888
	ds_read_b128 v[192:195], v190 offset:38912
	ds_read_b128 v[196:199], v190 offset:39936
	global_load_lds_dwordx4 v[200:201], off
	v_lshl_add_u64 v[200:201], s[54:55], 0, v[156:157]
	s_mov_b32 m0, s42
	s_nop 0
	global_load_lds_dwordx4 v[200:201], off
	s_waitcnt lgkmcnt(8)
	s_barrier
	s_waitcnt lgkmcnt(0)
	s_setprio 1
	s_waitcnt lgkmcnt(0)
	v_mfma_f32_16x16x32_bf16 v[124:127], v[128:131], v[144:147], v[124:127]
	v_mfma_f32_16x16x32_bf16 v[120:123], v[136:139], v[144:147], v[120:123]
	v_mfma_f32_16x16x32_bf16 v[108:111], v[128:131], v[168:171], v[108:111]
	v_mfma_f32_16x16x32_bf16 v[104:107], v[136:139], v[168:171], v[104:107]
	v_mfma_f32_16x16x32_bf16 v[92:95], v[128:131], v[176:179], v[92:95]
	v_mfma_f32_16x16x32_bf16 v[88:91], v[136:139], v[176:179], v[88:91]
	v_mfma_f32_16x16x32_bf16 v[76:79], v[128:131], v[192:195], v[76:79]
	v_mfma_f32_16x16x32_bf16 v[72:75], v[136:139], v[192:195], v[72:75]
	v_mfma_f32_16x16x32_bf16 v[124:127], v[132:135], v[148:151], v[124:127]
	v_mfma_f32_16x16x32_bf16 v[120:123], v[140:143], v[148:151], v[120:123]
	v_mfma_f32_16x16x32_bf16 v[108:111], v[132:135], v[172:175], v[108:111]
	v_mfma_f32_16x16x32_bf16 v[104:107], v[140:143], v[172:175], v[104:107]
	v_mfma_f32_16x16x32_bf16 v[92:95], v[132:135], v[180:183], v[92:95]
	v_mfma_f32_16x16x32_bf16 v[88:91], v[140:143], v[180:183], v[88:91]
	v_mfma_f32_16x16x32_bf16 v[76:79], v[132:135], v[196:199], v[76:79]
	v_mfma_f32_16x16x32_bf16 v[72:75], v[140:143], v[196:199], v[72:75]
	s_setprio 0
	s_barrier
	s_add_i32 s54, 0, 0x1c000
	s_add_i32 s55, s61, s33
	v_add_u32_e32 v214, s54, v187
	v_lshl_add_u64 v[184:185], v[184:185], 0, s[18:19]
	s_mov_b32 m0, s55
	ds_read_b128 v[200:203], v214
	ds_read_b128 v[206:209], v214 offset:1024
	ds_read_b128 v[210:213], v214 offset:2048
	ds_read_b128 v[214:217], v214 offset:3072
	global_load_lds_dwordx4 v[184:185], off
	v_lshl_add_u64 v[184:185], v[218:219], 0, s[18:19]
	s_add_i32 m0, s55, 0x2000
	s_nop 0
	global_load_lds_dwordx4 v[184:185], off
	s_barrier
	s_waitcnt lgkmcnt(0)
	s_setprio 1
	s_waitcnt lgkmcnt(0)
	v_mfma_f32_16x16x32_bf16 v[116:119], v[200:203], v[144:147], v[116:119]
	v_mfma_f32_16x16x32_bf16 v[112:115], v[210:213], v[144:147], v[112:115]
	v_mfma_f32_16x16x32_bf16 v[100:103], v[200:203], v[168:171], v[100:103]
	v_mfma_f32_16x16x32_bf16 v[96:99], v[210:213], v[168:171], v[96:99]
	v_mfma_f32_16x16x32_bf16 v[84:87], v[200:203], v[176:179], v[84:87]
	v_mfma_f32_16x16x32_bf16 v[80:83], v[210:213], v[176:179], v[80:83]
	v_mfma_f32_16x16x32_bf16 v[68:71], v[200:203], v[192:195], v[68:71]
	v_mfma_f32_16x16x32_bf16 v[64:67], v[210:213], v[192:195], v[64:67]
	v_mfma_f32_16x16x32_bf16 v[116:119], v[206:209], v[148:151], v[116:119]
	v_mfma_f32_16x16x32_bf16 v[112:115], v[214:217], v[148:151], v[112:115]
	v_mfma_f32_16x16x32_bf16 v[100:103], v[206:209], v[172:175], v[100:103]
	v_mfma_f32_16x16x32_bf16 v[96:99], v[214:217], v[172:175], v[96:99]
	v_mfma_f32_16x16x32_bf16 v[84:87], v[206:209], v[180:183], v[84:87]
	v_mfma_f32_16x16x32_bf16 v[80:83], v[214:217], v[180:183], v[80:83]
	v_mfma_f32_16x16x32_bf16 v[68:71], v[206:209], v[196:199], v[68:71]
	v_mfma_f32_16x16x32_bf16 v[64:67], v[214:217], v[196:199], v[64:67]
	s_setprio 0
	s_mov_b32 m0, s44
	v_lshl_add_u64 v[184:185], v[220:221], 0, s[18:19]
	s_barrier
	ds_read_b128 v[144:147], v190 offset:49152
	ds_read_b128 v[148:151], v190 offset:50176
	ds_read_b128 v[168:171], v190 offset:51200
	ds_read_b128 v[172:175], v190 offset:52224
	ds_read_b128 v[176:179], v190 offset:53248
	ds_read_b128 v[180:183], v190 offset:54272
	ds_read_b128 v[192:195], v190 offset:55296
	ds_read_b128 v[196:199], v190 offset:56320
	global_load_lds_dwordx4 v[184:185], off
	v_lshl_add_u64 v[184:185], v[222:223], 0, s[18:19]
	s_mov_b32 m0, s45
	s_nop 0
	global_load_lds_dwordx4 v[184:185], off
	s_barrier
	s_waitcnt lgkmcnt(0)
	s_setprio 1
	s_waitcnt lgkmcnt(0)
	v_mfma_f32_16x16x32_bf16 v[60:63], v[128:131], v[144:147], v[60:63]
	v_mfma_f32_16x16x32_bf16 v[56:59], v[136:139], v[144:147], v[56:59]
	v_mfma_f32_16x16x32_bf16 v[44:47], v[128:131], v[168:171], v[44:47]
	v_mfma_f32_16x16x32_bf16 v[40:43], v[136:139], v[168:171], v[40:43]
	v_mfma_f32_16x16x32_bf16 v[28:31], v[128:131], v[176:179], v[28:31]
	v_mfma_f32_16x16x32_bf16 v[24:27], v[136:139], v[176:179], v[24:27]
	v_mfma_f32_16x16x32_bf16 v[12:15], v[128:131], v[192:195], v[12:15]
	v_mfma_f32_16x16x32_bf16 v[8:11], v[136:139], v[192:195], v[8:11]
	v_mfma_f32_16x16x32_bf16 v[60:63], v[132:135], v[148:151], v[60:63]
	v_mfma_f32_16x16x32_bf16 v[56:59], v[140:143], v[148:151], v[56:59]
	v_mfma_f32_16x16x32_bf16 v[44:47], v[132:135], v[172:175], v[44:47]
	v_mfma_f32_16x16x32_bf16 v[40:43], v[140:143], v[172:175], v[40:43]
	v_mfma_f32_16x16x32_bf16 v[28:31], v[132:135], v[180:183], v[28:31]
	v_mfma_f32_16x16x32_bf16 v[24:27], v[140:143], v[180:183], v[24:27]
	v_mfma_f32_16x16x32_bf16 v[12:15], v[132:135], v[196:199], v[12:15]
	v_mfma_f32_16x16x32_bf16 v[8:11], v[140:143], v[196:199], v[8:11]
	s_setprio 0
	s_barrier
	s_add_u32 s52, s52, 0x100080
	s_addc_u32 s53, s53, 0
	s_add_i32 s54, s54, s33
	v_lshl_add_u64 v[128:129], s[52:53], 0, v[154:155]
	s_mov_b32 m0, s54
	s_nop 0
	global_load_lds_dwordx4 v[128:129], off
	v_lshl_add_u64 v[128:129], s[52:53], 0, v[158:159]
	s_add_i32 m0, s54, 0x2000
	s_nop 0
	global_load_lds_dwordx4 v[128:129], off
	s_waitcnt vmcnt(6)
	s_barrier
	s_setprio 1
	v_mfma_f32_16x16x32_bf16 v[52:55], v[200:203], v[144:147], v[52:55]
	v_mfma_f32_16x16x32_bf16 v[48:51], v[210:213], v[144:147], v[48:51]
	v_mfma_f32_16x16x32_bf16 v[36:39], v[200:203], v[168:171], v[36:39]
	v_mfma_f32_16x16x32_bf16 v[32:35], v[210:213], v[168:171], v[32:35]
	v_mfma_f32_16x16x32_bf16 v[20:23], v[200:203], v[176:179], v[20:23]
	v_mfma_f32_16x16x32_bf16 v[16:19], v[210:213], v[176:179], v[16:19]
	v_mfma_f32_16x16x32_bf16 v[4:7], v[200:203], v[192:195], v[4:7]
	v_mfma_f32_16x16x32_bf16 v[0:3], v[210:213], v[192:195], v[0:3]
	v_mfma_f32_16x16x32_bf16 v[52:55], v[206:209], v[148:151], v[52:55]
	v_mfma_f32_16x16x32_bf16 v[48:51], v[214:217], v[148:151], v[48:51]
	v_mfma_f32_16x16x32_bf16 v[36:39], v[206:209], v[172:175], v[36:39]
	v_mfma_f32_16x16x32_bf16 v[32:35], v[214:217], v[172:175], v[32:35]
	v_mfma_f32_16x16x32_bf16 v[20:23], v[206:209], v[180:183], v[20:23]
	v_mfma_f32_16x16x32_bf16 v[16:19], v[214:217], v[180:183], v[16:19]
	v_mfma_f32_16x16x32_bf16 v[4:7], v[206:209], v[196:199], v[4:7]
	v_mfma_f32_16x16x32_bf16 v[0:3], v[214:217], v[196:199], v[0:3]
	s_setprio 0
	s_add_i32 s60, s60, 2
	s_add_u32 s50, s50, 0x100
	s_addc_u32 s51, s51, 0
	s_add_u32 s58, s58, 0x100
	s_addc_u32 s59, s59, 0
	s_cmp_gt_u32 s60, 61
	s_barrier

.LBB0_1140:
	s_ashr_i32 s61, s60, 31
	v_cmp_lt_i64_e32 vcc, s[62:63], v[140:141]
	s_lshl_b64 s[62:63], s[60:61], 19
	s_add_u32 s62, s1, s62
	s_addc_u32 s63, s2, s63
	s_and_b64 s[64:65], vcc, exec
	s_cselect_b32 s11, s63, s13
	s_cselect_b32 s61, s62, s12
	s_ashr_i32 s59, s58, 31
	s_lshl_b64 s[64:65], s[58:59], 19
	s_add_u32 s64, s50, s64
	s_addc_u32 s65, s51, s65
	s_and_b64 s[68:69], vcc, exec
	s_cselect_b32 s59, s65, s67
	s_cselect_b32 s74, s64, s66
	s_add_u32 s12, s12, 0x40080
	s_addc_u32 s13, s13, 0
	s_add_u32 s75, s66, 0x100

	s_addc_u32 s76, s67, 0
	s_mov_b32 s77, -2


	ds_read_b128 v[144:147], v159
	ds_read_b128 v[150:153], v159 offset:1024
	ds_read_b128 v[164:167], v159 offset:2048
	ds_read_b128 v[168:171], v159 offset:3072
	s_add_u32 s66, s12, 0xfffc0080
	s_addc_u32 s67, s13, -1
	s_cmp_eq_u32 s77, 12
	s_cselect_b32 s69, s11, s67
	s_cselect_b32 s68, s61, s66
	s_cselect_b32 s67, s59, s76
	s_cselect_b32 s66, s74, s75
	v_lshl_add_u64 v[154:155], s[12:13], 0, v[136:137]
	s_add_i32 m0, s34, 0xc000
	ds_read_b128 v[172:175], v160
	ds_read_b128 v[176:179], v160 offset:1024
	ds_read_b128 v[180:183], v160 offset:2048
	ds_read_b128 v[184:187], v160 offset:3072
	ds_read_b128 v[188:191], v160 offset:4096
	ds_read_b128 v[192:195], v160 offset:5120
	ds_read_b128 v[196:199], v160 offset:6144
	ds_read_b128 v[200:203], v160 offset:7168
	global_load_lds_dwordx4 v[154:155], off
	v_lshl_add_u64 v[154:155], s[12:13], 0, v[138:139]
	s_add_i32 m0, s34, 0xe000
	s_nop 0
	global_load_lds_dwordx4 v[154:155], off
	s_waitcnt lgkmcnt(8)
	s_barrier
	s_waitcnt lgkmcnt(0)
	s_setprio 1
	s_waitcnt lgkmcnt(0)
	v_mfma_f32_16x16x32_bf16 v[124:127], v[144:147], v[172:175], 0
	v_mfma_f32_16x16x32_bf16 v[120:123], v[164:167], v[172:175], 0
	v_mfma_f32_16x16x32_bf16 v[116:119], v[144:147], v[180:183], 0
	v_mfma_f32_16x16x32_bf16 v[108:111], v[164:167], v[180:183], 0
	v_mfma_f32_16x16x32_bf16 v[100:103], v[144:147], v[188:191], 0
	v_mfma_f32_16x16x32_bf16 v[92:95], v[164:167], v[188:191], 0
	v_mfma_f32_16x16x32_bf16 v[84:87], v[144:147], v[196:199], 0
	v_mfma_f32_16x16x32_bf16 v[76:79], v[164:167], v[196:199], 0
	v_mfma_f32_16x16x32_bf16 v[124:127], v[150:153], v[176:179], v[124:127]
	v_mfma_f32_16x16x32_bf16 v[120:123], v[168:171], v[176:179], v[120:123]
	v_mfma_f32_16x16x32_bf16 v[116:119], v[150:153], v[184:187], v[116:119]
	v_mfma_f32_16x16x32_bf16 v[108:111], v[168:171], v[184:187], v[108:111]
	v_mfma_f32_16x16x32_bf16 v[100:103], v[150:153], v[192:195], v[100:103]
	v_mfma_f32_16x16x32_bf16 v[92:95], v[168:171], v[192:195], v[92:95]
	v_mfma_f32_16x16x32_bf16 v[84:87], v[150:153], v[200:203], v[84:87]
	v_mfma_f32_16x16x32_bf16 v[76:79], v[168:171], v[200:203], v[76:79]
	s_setprio 0
	s_barrier
	s_add_i32 s78, s49, s20
	v_lshl_add_u64 v[154:155], s[66:67], 0, v[132:133]
	s_mov_b32 m0, s78
	ds_read_b128 v[206:209], v161
	ds_read_b128 v[210:213], v161 offset:1024
	ds_read_b128 v[214:217], v161 offset:2048
	ds_read_b128 v[218:221], v161 offset:3072
	global_load_lds_dwordx4 v[154:155], off
	v_lshl_add_u64 v[222:223], s[66:67], 0, v[128:129]
	s_add_i32 m0, s78, 0x2000
	s_nop 0
	global_load_lds_dwordx4 v[222:223], off
	s_barrier
	s_waitcnt lgkmcnt(0)
	s_setprio 1
	s_waitcnt lgkmcnt(0)
	v_mfma_f32_16x16x32_bf16 v[112:115], v[206:209], v[172:175], 0
	v_mfma_f32_16x16x32_bf16 v[104:107], v[214:217], v[172:175], 0
	v_mfma_f32_16x16x32_bf16 v[96:99], v[206:209], v[180:183], 0
	v_mfma_f32_16x16x32_bf16 v[88:91], v[214:217], v[180:183], 0
	v_mfma_f32_16x16x32_bf16 v[80:83], v[206:209], v[188:191], 0
	v_mfma_f32_16x16x32_bf16 v[72:75], v[214:217], v[188:191], 0
	v_mfma_f32_16x16x32_bf16 v[68:71], v[206:209], v[196:199], 0
	v_mfma_f32_16x16x32_bf16 v[64:67], v[214:217], v[196:199], 0
	v_mfma_f32_16x16x32_bf16 v[112:115], v[210:213], v[176:179], v[112:115]
	v_mfma_f32_16x16x32_bf16 v[104:107], v[218:221], v[176:179], v[104:107]
	v_mfma_f32_16x16x32_bf16 v[96:99], v[210:213], v[184:187], v[96:99]
	v_mfma_f32_16x16x32_bf16 v[88:91], v[218:221], v[184:187], v[88:91]
	v_mfma_f32_16x16x32_bf16 v[80:83], v[210:213], v[192:195], v[80:83]
	v_mfma_f32_16x16x32_bf16 v[72:75], v[218:221], v[192:195], v[72:75]
	v_mfma_f32_16x16x32_bf16 v[68:71], v[210:213], v[200:203], v[68:71]
	v_mfma_f32_16x16x32_bf16 v[64:67], v[218:221], v[200:203], v[64:67]
	s_setprio 0
	s_mov_b32 m0, s34
	v_lshl_add_u64 v[224:225], s[68:69], 0, v[134:135]
	s_barrier
	ds_read_b128 v[172:175], v160 offset:16384
	ds_read_b128 v[176:179], v160 offset:17408
	ds_read_b128 v[180:183], v160 offset:18432
	ds_read_b128 v[184:187], v160 offset:19456
	ds_read_b128 v[188:191], v160 offset:20480
	ds_read_b128 v[192:195], v160 offset:21504
	ds_read_b128 v[196:199], v160 offset:22528
	ds_read_b128 v[200:203], v160 offset:23552
	global_load_lds_dwordx4 v[224:225], off
	v_lshl_add_u64 v[226:227], s[68:69], 0, v[130:131]
	s_mov_b32 m0, s35
	s_nop 0
	global_load_lds_dwordx4 v[226:227], off
	s_barrier
	s_waitcnt lgkmcnt(0)
	s_setprio 1
	s_waitcnt lgkmcnt(0)
	v_mfma_f32_16x16x32_bf16 v[60:63], v[144:147], v[172:175], 0
	v_mfma_f32_16x16x32_bf16 v[56:59], v[164:167], v[172:175], 0
	v_mfma_f32_16x16x32_bf16 v[52:55], v[144:147], v[180:183], 0
	v_mfma_f32_16x16x32_bf16 v[44:47], v[164:167], v[180:183], 0
	v_mfma_f32_16x16x32_bf16 v[36:39], v[144:147], v[188:191], 0
	v_mfma_f32_16x16x32_bf16 v[28:31], v[164:167], v[188:191], 0
	v_mfma_f32_16x16x32_bf16 v[20:23], v[144:147], v[196:199], 0
	v_mfma_f32_16x16x32_bf16 v[12:15], v[164:167], v[196:199], 0
	v_mfma_f32_16x16x32_bf16 v[60:63], v[150:153], v[176:179], v[60:63]
	v_mfma_f32_16x16x32_bf16 v[56:59], v[168:171], v[176:179], v[56:59]
	v_mfma_f32_16x16x32_bf16 v[52:55], v[150:153], v[184:187], v[52:55]
	v_mfma_f32_16x16x32_bf16 v[44:47], v[168:171], v[184:187], v[44:47]
	v_mfma_f32_16x16x32_bf16 v[36:39], v[150:153], v[192:195], v[36:39]
	v_mfma_f32_16x16x32_bf16 v[28:31], v[168:171], v[192:195], v[28:31]
	v_mfma_f32_16x16x32_bf16 v[20:23], v[150:153], v[200:203], v[20:23]
	v_mfma_f32_16x16x32_bf16 v[12:15], v[168:171], v[200:203], v[12:15]
	s_setprio 0
	s_barrier
	s_add_u32 s78, s66, 0x40000
	s_addc_u32 s79, s67, 0
	s_add_i32 s80, s70, s20
	v_lshl_add_u64 v[144:145], s[78:79], 0, v[132:133]
	s_mov_b32 m0, s80
	s_nop 0
	global_load_lds_dwordx4 v[144:145], off
	v_lshl_add_u64 v[144:145], s[78:79], 0, v[128:129]
	s_add_i32 m0, s80, 0x2000
	s_nop 0
	global_load_lds_dwordx4 v[144:145], off
	s_waitcnt vmcnt(6)
	s_barrier
	s_setprio 1
	v_mfma_f32_16x16x32_bf16 v[48:51], v[206:209], v[172:175], 0
	v_mfma_f32_16x16x32_bf16 v[40:43], v[214:217], v[172:175], 0
	v_mfma_f32_16x16x32_bf16 v[32:35], v[206:209], v[180:183], 0
	v_mfma_f32_16x16x32_bf16 v[24:27], v[214:217], v[180:183], 0
	v_mfma_f32_16x16x32_bf16 v[16:19], v[206:209], v[188:191], 0
	v_mfma_f32_16x16x32_bf16 v[8:11], v[214:217], v[188:191], 0
	v_mfma_f32_16x16x32_bf16 v[4:7], v[206:209], v[196:199], 0
	v_mfma_f32_16x16x32_bf16 v[0:3], v[214:217], v[196:199], 0
	v_mfma_f32_16x16x32_bf16 v[48:51], v[210:213], v[176:179], v[48:51]
	v_mfma_f32_16x16x32_bf16 v[40:43], v[218:221], v[176:179], v[40:43]
	v_mfma_f32_16x16x32_bf16 v[32:35], v[210:213], v[184:187], v[32:35]
	v_mfma_f32_16x16x32_bf16 v[24:27], v[218:221], v[184:187], v[24:27]
	v_mfma_f32_16x16x32_bf16 v[16:19], v[210:213], v[192:195], v[16:19]
	v_mfma_f32_16x16x32_bf16 v[8:11], v[218:221], v[192:195], v[8:11]
	v_mfma_f32_16x16x32_bf16 v[4:7], v[210:213], v[200:203], v[4:7]
	v_mfma_f32_16x16x32_bf16 v[0:3], v[218:221], v[200:203], v[0:3]
	s_setprio 0
	s_add_i32 s78, 0, 0x18000
	v_add_u32_e32 v148, s78, v157
	s_barrier
	ds_read_b128 v[144:147], v148
	ds_read_b128 v[150:153], v148 offset:1024
	ds_read_b128 v[164:167], v148 offset:2048
	ds_read_b128 v[168:171], v148 offset:3072
	s_add_u32 s68, s68, 0x40000
	s_addc_u32 s69, s69, 0
	s_mov_b32 m0, s42
	v_lshl_add_u64 v[206:207], s[68:69], 0, v[134:135]
	ds_read_b128 v[172:175], v160 offset:32768
	ds_read_b128 v[176:179], v160 offset:33792
	ds_read_b128 v[180:183], v160 offset:34816
	ds_read_b128 v[184:187], v160 offset:35840
	ds_read_b128 v[188:191], v160 offset:36864
	ds_read_b128 v[192:195], v160 offset:37888
	ds_read_b128 v[196:199], v160 offset:38912
	ds_read_b128 v[200:203], v160 offset:39936
	global_load_lds_dwordx4 v[206:207], off
	v_lshl_add_u64 v[206:207], s[68:69], 0, v[130:131]
	s_mov_b32 m0, s43
	s_nop 0
	global_load_lds_dwordx4 v[206:207], off
	s_waitcnt lgkmcnt(8)
	s_barrier
	s_waitcnt lgkmcnt(0)
	s_setprio 1
	s_waitcnt lgkmcnt(0)
	v_mfma_f32_16x16x32_bf16 v[124:127], v[144:147], v[172:175], v[124:127]
	v_mfma_f32_16x16x32_bf16 v[120:123], v[164:167], v[172:175], v[120:123]
	v_mfma_f32_16x16x32_bf16 v[116:119], v[144:147], v[180:183], v[116:119]
	v_mfma_f32_16x16x32_bf16 v[108:111], v[164:167], v[180:183], v[108:111]
	v_mfma_f32_16x16x32_bf16 v[100:103], v[144:147], v[188:191], v[100:103]
	v_mfma_f32_16x16x32_bf16 v[92:95], v[164:167], v[188:191], v[92:95]
	v_mfma_f32_16x16x32_bf16 v[84:87], v[144:147], v[196:199], v[84:87]
	v_mfma_f32_16x16x32_bf16 v[76:79], v[164:167], v[196:199], v[76:79]
	v_mfma_f32_16x16x32_bf16 v[124:127], v[150:153], v[176:179], v[124:127]
	v_mfma_f32_16x16x32_bf16 v[120:123], v[168:171], v[176:179], v[120:123]
	v_mfma_f32_16x16x32_bf16 v[116:119], v[150:153], v[184:187], v[116:119]
	v_mfma_f32_16x16x32_bf16 v[108:111], v[168:171], v[184:187], v[108:111]
	v_mfma_f32_16x16x32_bf16 v[100:103], v[150:153], v[192:195], v[100:103]
	v_mfma_f32_16x16x32_bf16 v[92:95], v[168:171], v[192:195], v[92:95]
	v_mfma_f32_16x16x32_bf16 v[84:87], v[150:153], v[200:203], v[84:87]
	v_mfma_f32_16x16x32_bf16 v[76:79], v[168:171], v[200:203], v[76:79]
	s_setprio 0
	s_barrier
	s_add_i32 s68, 0, 0x1c000
	s_add_i32 s69, s78, s20
	v_add_u32_e32 v148, s68, v157
	v_lshl_add_u64 v[154:155], v[154:155], 0, s[56:57]
	s_mov_b32 m0, s69
	ds_read_b128 v[206:209], v148
	ds_read_b128 v[210:213], v148 offset:1024
	ds_read_b128 v[214:217], v148 offset:2048
	ds_read_b128 v[218:221], v148 offset:3072
	global_load_lds_dwordx4 v[154:155], off
	v_lshl_add_u64 v[154:155], v[222:223], 0, s[56:57]
	s_add_i32 m0, s69, 0x2000
	s_nop 0
	global_load_lds_dwordx4 v[154:155], off
	s_barrier
	s_waitcnt lgkmcnt(0)
	s_setprio 1
	s_waitcnt lgkmcnt(0)
	v_mfma_f32_16x16x32_bf16 v[112:115], v[206:209], v[172:175], v[112:115]
	v_mfma_f32_16x16x32_bf16 v[104:107], v[214:217], v[172:175], v[104:107]
	v_mfma_f32_16x16x32_bf16 v[96:99], v[206:209], v[180:183], v[96:99]
	v_mfma_f32_16x16x32_bf16 v[88:91], v[214:217], v[180:183], v[88:91]
	v_mfma_f32_16x16x32_bf16 v[80:83], v[206:209], v[188:191], v[80:83]
	v_mfma_f32_16x16x32_bf16 v[72:75], v[214:217], v[188:191], v[72:75]
	v_mfma_f32_16x16x32_bf16 v[68:71], v[206:209], v[196:199], v[68:71]
	v_mfma_f32_16x16x32_bf16 v[64:67], v[214:217], v[196:199], v[64:67]
	v_mfma_f32_16x16x32_bf16 v[112:115], v[210:213], v[176:179], v[112:115]
	v_mfma_f32_16x16x32_bf16 v[104:107], v[218:221], v[176:179], v[104:107]
	v_mfma_f32_16x16x32_bf16 v[96:99], v[210:213], v[184:187], v[96:99]
	v_mfma_f32_16x16x32_bf16 v[88:91], v[218:221], v[184:187], v[88:91]
	v_mfma_f32_16x16x32_bf16 v[80:83], v[210:213], v[192:195], v[80:83]
	v_mfma_f32_16x16x32_bf16 v[72:75], v[218:221], v[192:195], v[72:75]
	v_mfma_f32_16x16x32_bf16 v[68:71], v[210:213], v[200:203], v[68:71]
	v_mfma_f32_16x16x32_bf16 v[64:67], v[218:221], v[200:203], v[64:67]
	s_setprio 0
	s_mov_b32 m0, s45
	v_lshl_add_u64 v[154:155], v[224:225], 0, s[56:57]
	s_barrier
	ds_read_b128 v[172:175], v160 offset:49152
	ds_read_b128 v[176:179], v160 offset:50176
	ds_read_b128 v[180:183], v160 offset:51200
	ds_read_b128 v[184:187], v160 offset:52224
	ds_read_b128 v[188:191], v160 offset:53248
	ds_read_b128 v[192:195], v160 offset:54272
	ds_read_b128 v[196:199], v160 offset:55296
	ds_read_b128 v[200:203], v160 offset:56320
	global_load_lds_dwordx4 v[154:155], off
	v_lshl_add_u64 v[154:155], v[226:227], 0, s[56:57]
	s_mov_b32 m0, s46
	s_nop 0
	global_load_lds_dwordx4 v[154:155], off
	s_barrier
	s_waitcnt lgkmcnt(0)
	s_setprio 1
	s_waitcnt lgkmcnt(0)
	v_mfma_f32_16x16x32_bf16 v[60:63], v[144:147], v[172:175], v[60:63]
	v_mfma_f32_16x16x32_bf16 v[56:59], v[164:167], v[172:175], v[56:59]
	v_mfma_f32_16x16x32_bf16 v[52:55], v[144:147], v[180:183], v[52:55]
	v_mfma_f32_16x16x32_bf16 v[44:47], v[164:167], v[180:183], v[44:47]
	v_mfma_f32_16x16x32_bf16 v[36:39], v[144:147], v[188:191], v[36:39]
	v_mfma_f32_16x16x32_bf16 v[28:31], v[164:167], v[188:191], v[28:31]
	v_mfma_f32_16x16x32_bf16 v[20:23], v[144:147], v[196:199], v[20:23]
	v_mfma_f32_16x16x32_bf16 v[12:15], v[164:167], v[196:199], v[12:15]
	v_mfma_f32_16x16x32_bf16 v[60:63], v[150:153], v[176:179], v[60:63]
	v_mfma_f32_16x16x32_bf16 v[56:59], v[168:171], v[176:179], v[56:59]
	v_mfma_f32_16x16x32_bf16 v[52:55], v[150:153], v[184:187], v[52:55]
	v_mfma_f32_16x16x32_bf16 v[44:47], v[168:171], v[184:187], v[44:47]
	v_mfma_f32_16x16x32_bf16 v[36:39], v[150:153], v[192:195], v[36:39]
	v_mfma_f32_16x16x32_bf16 v[28:31], v[168:171], v[192:195], v[28:31]
	v_mfma_f32_16x16x32_bf16 v[20:23], v[150:153], v[200:203], v[20:23]
	v_mfma_f32_16x16x32_bf16 v[12:15], v[168:171], v[200:203], v[12:15]
	s_setprio 0
	s_barrier
	s_add_u32 s66, s66, 0x40080
	s_addc_u32 s67, s67, 0
	s_add_i32 s68, s68, s20
	v_lshl_add_u64 v[144:145], s[66:67], 0, v[132:133]
	s_mov_b32 m0, s68
	s_nop 0
	global_load_lds_dwordx4 v[144:145], off
	v_lshl_add_u64 v[144:145], s[66:67], 0, v[128:129]
	s_add_i32 m0, s68, 0x2000
	s_nop 0
	global_load_lds_dwordx4 v[144:145], off
	s_waitcnt vmcnt(6)
	s_barrier
	s_setprio 1
	v_mfma_f32_16x16x32_bf16 v[48:51], v[206:209], v[172:175], v[48:51]
	v_mfma_f32_16x16x32_bf16 v[40:43], v[214:217], v[172:175], v[40:43]
	v_mfma_f32_16x16x32_bf16 v[32:35], v[206:209], v[180:183], v[32:35]
	v_mfma_f32_16x16x32_bf16 v[24:27], v[214:217], v[180:183], v[24:27]
	v_mfma_f32_16x16x32_bf16 v[16:19], v[206:209], v[188:191], v[16:19]
	v_mfma_f32_16x16x32_bf16 v[8:11], v[214:217], v[188:191], v[8:11]
	v_mfma_f32_16x16x32_bf16 v[4:7], v[206:209], v[196:199], v[4:7]
	v_mfma_f32_16x16x32_bf16 v[0:3], v[214:217], v[196:199], v[0:3]
	v_mfma_f32_16x16x32_bf16 v[48:51], v[210:213], v[176:179], v[48:51]
	v_mfma_f32_16x16x32_bf16 v[40:43], v[218:221], v[176:179], v[40:43]
	v_mfma_f32_16x16x32_bf16 v[32:35], v[210:213], v[184:187], v[32:35]
	v_mfma_f32_16x16x32_bf16 v[24:27], v[218:221], v[184:187], v[24:27]
	v_mfma_f32_16x16x32_bf16 v[16:19], v[210:213], v[192:195], v[16:19]
	v_mfma_f32_16x16x32_bf16 v[8:11], v[218:221], v[192:195], v[8:11]
	v_mfma_f32_16x16x32_bf16 v[4:7], v[210:213], v[200:203], v[4:7]
	v_mfma_f32_16x16x32_bf16 v[0:3], v[218:221], v[200:203], v[0:3]
	s_setprio 0
	s_add_i32 s77, s77, 2
	s_add_u32 s12, s12, 0x100
	s_addc_u32 s13, s13, 0
	s_add_u32 s75, s75, 0x100
	s_addc_u32 s76, s76, 0
	s_cmp_gt_u32 s77, 13
	s_barrier

.LBB0_1893:
	s_ashr_i32 s29, s28, 31
	v_cmp_lt_i64_e32 vcc, s[30:31], v[164:165]
	s_lshl_b64 s[30:31], s[28:29], 19
	s_add_u32 s30, s12, s30
	s_addc_u32 s31, s13, s31
	s_and_b64 s[34:35], vcc, exec
	s_cselect_b32 s29, s31, s41
	s_cselect_b32 s37, s30, s40
	s_ashr_i32 s27, s26, 31
	s_lshl_b64 s[34:35], s[26:27], 19
	s_add_u32 s34, s1, s34
	s_addc_u32 s35, s2, s35
	s_and_b64 s[44:45], vcc, exec
	s_cselect_b32 s27, s35, s43
	s_cselect_b32 s54, s34, s42
	s_add_u32 s40, s40, 0x40080
	s_addc_u32 s41, s41, 0
	s_add_u32 s55, s42, 0x100

	s_addc_u32 s56, s43, 0
	s_mov_b32 s57, -2
	s_waitcnt lgkmcnt(0)


	ds_read_b128 v[128:131], v189
	ds_read_b128 v[132:135], v189 offset:1024
	ds_read_b128 v[136:139], v189 offset:2048
	ds_read_b128 v[140:143], v189 offset:3072
	s_add_u32 s42, s40, 0xfffc0080
	s_addc_u32 s43, s41, -1
	s_cmp_eq_u32 s57, 12
	s_cselect_b32 s45, s29, s43
	s_cselect_b32 s44, s37, s42
	s_cselect_b32 s43, s27, s56
	s_cselect_b32 s42, s54, s55
	v_lshl_add_u64 v[184:185], s[40:41], 0, v[160:161]
	s_add_i32 m0, s20, 0xc000
	ds_read_b128 v[144:147], v190
	ds_read_b128 v[148:151], v190 offset:1024
	ds_read_b128 v[168:171], v190 offset:2048
	ds_read_b128 v[172:175], v190 offset:3072
	ds_read_b128 v[176:179], v190 offset:4096
	ds_read_b128 v[180:183], v190 offset:5120
	ds_read_b128 v[192:195], v190 offset:6144
	ds_read_b128 v[196:199], v190 offset:7168
	global_load_lds_dwordx4 v[184:185], off
	v_lshl_add_u64 v[184:185], s[40:41], 0, v[162:163]
	s_add_i32 m0, s20, 0xe000
	s_nop 0
	global_load_lds_dwordx4 v[184:185], off
	s_waitcnt lgkmcnt(8)
	s_barrier
	s_waitcnt lgkmcnt(0)
	s_setprio 1
	s_waitcnt lgkmcnt(0)
	v_mfma_f32_16x16x32_bf16 v[124:127], v[128:131], v[144:147], 0
	v_mfma_f32_16x16x32_bf16 v[120:123], v[136:139], v[144:147], 0
	v_mfma_f32_16x16x32_bf16 v[108:111], v[128:131], v[168:171], 0
	v_mfma_f32_16x16x32_bf16 v[104:107], v[136:139], v[168:171], 0
	v_mfma_f32_16x16x32_bf16 v[92:95], v[128:131], v[176:179], 0
	v_mfma_f32_16x16x32_bf16 v[88:91], v[136:139], v[176:179], 0
	v_mfma_f32_16x16x32_bf16 v[76:79], v[128:131], v[192:195], 0
	v_mfma_f32_16x16x32_bf16 v[72:75], v[136:139], v[192:195], 0
	v_mfma_f32_16x16x32_bf16 v[124:127], v[132:135], v[148:151], v[124:127]
	v_mfma_f32_16x16x32_bf16 v[120:123], v[140:143], v[148:151], v[120:123]
	v_mfma_f32_16x16x32_bf16 v[108:111], v[132:135], v[172:175], v[108:111]
	v_mfma_f32_16x16x32_bf16 v[104:107], v[140:143], v[172:175], v[104:107]
	v_mfma_f32_16x16x32_bf16 v[92:95], v[132:135], v[180:183], v[92:95]
	v_mfma_f32_16x16x32_bf16 v[88:91], v[140:143], v[180:183], v[88:91]
	v_mfma_f32_16x16x32_bf16 v[76:79], v[132:135], v[196:199], v[76:79]
	v_mfma_f32_16x16x32_bf16 v[72:75], v[140:143], v[196:199], v[72:75]
	s_setprio 0
	s_barrier
	s_add_i32 s58, s52, s3
	v_lshl_add_u64 v[184:185], s[42:43], 0, v[154:155]
	s_mov_b32 m0, s58
	ds_read_b128 v[200:203], v191
	ds_read_b128 v[206:209], v191 offset:1024
	ds_read_b128 v[210:213], v191 offset:2048
	ds_read_b128 v[214:217], v191 offset:3072
	global_load_lds_dwordx4 v[184:185], off
	v_lshl_add_u64 v[218:219], s[42:43], 0, v[158:159]
	s_add_i32 m0, s58, 0x2000
	s_nop 0
	global_load_lds_dwordx4 v[218:219], off
	s_barrier
	s_waitcnt lgkmcnt(0)
	s_setprio 1
	s_waitcnt lgkmcnt(0)
	v_mfma_f32_16x16x32_bf16 v[116:119], v[200:203], v[144:147], 0
	v_mfma_f32_16x16x32_bf16 v[112:115], v[210:213], v[144:147], 0
	v_mfma_f32_16x16x32_bf16 v[100:103], v[200:203], v[168:171], 0
	v_mfma_f32_16x16x32_bf16 v[96:99], v[210:213], v[168:171], 0
	v_mfma_f32_16x16x32_bf16 v[84:87], v[200:203], v[176:179], 0
	v_mfma_f32_16x16x32_bf16 v[80:83], v[210:213], v[176:179], 0
	v_mfma_f32_16x16x32_bf16 v[68:71], v[200:203], v[192:195], 0
	v_mfma_f32_16x16x32_bf16 v[64:67], v[210:213], v[192:195], 0
	v_mfma_f32_16x16x32_bf16 v[116:119], v[206:209], v[148:151], v[116:119]
	v_mfma_f32_16x16x32_bf16 v[112:115], v[214:217], v[148:151], v[112:115]
	v_mfma_f32_16x16x32_bf16 v[100:103], v[206:209], v[172:175], v[100:103]
	v_mfma_f32_16x16x32_bf16 v[96:99], v[214:217], v[172:175], v[96:99]
	v_mfma_f32_16x16x32_bf16 v[84:87], v[206:209], v[180:183], v[84:87]
	v_mfma_f32_16x16x32_bf16 v[80:83], v[214:217], v[180:183], v[80:83]
	v_mfma_f32_16x16x32_bf16 v[68:71], v[206:209], v[196:199], v[68:71]
	v_mfma_f32_16x16x32_bf16 v[64:67], v[214:217], v[196:199], v[64:67]
	s_setprio 0
	s_mov_b32 m0, s20
	v_lshl_add_u64 v[220:221], s[44:45], 0, v[152:153]
	s_barrier
	ds_read_b128 v[144:147], v190 offset:16384
	ds_read_b128 v[148:151], v190 offset:17408
	ds_read_b128 v[168:171], v190 offset:18432
	ds_read_b128 v[172:175], v190 offset:19456
	ds_read_b128 v[176:179], v190 offset:20480
	ds_read_b128 v[180:183], v190 offset:21504
	ds_read_b128 v[192:195], v190 offset:22528
	ds_read_b128 v[196:199], v190 offset:23552
	global_load_lds_dwordx4 v[220:221], off
	v_lshl_add_u64 v[222:223], s[44:45], 0, v[156:157]
	s_mov_b32 m0, s21
	s_nop 0
	global_load_lds_dwordx4 v[222:223], off
	s_barrier
	s_waitcnt lgkmcnt(0)
	s_setprio 1
	s_waitcnt lgkmcnt(0)
	v_mfma_f32_16x16x32_bf16 v[60:63], v[128:131], v[144:147], 0
	v_mfma_f32_16x16x32_bf16 v[56:59], v[136:139], v[144:147], 0
	v_mfma_f32_16x16x32_bf16 v[44:47], v[128:131], v[168:171], 0
	v_mfma_f32_16x16x32_bf16 v[40:43], v[136:139], v[168:171], 0
	v_mfma_f32_16x16x32_bf16 v[28:31], v[128:131], v[176:179], 0
	v_mfma_f32_16x16x32_bf16 v[24:27], v[136:139], v[176:179], 0
	v_mfma_f32_16x16x32_bf16 v[12:15], v[128:131], v[192:195], 0
	v_mfma_f32_16x16x32_bf16 v[8:11], v[136:139], v[192:195], 0
	v_mfma_f32_16x16x32_bf16 v[60:63], v[132:135], v[148:151], v[60:63]
	v_mfma_f32_16x16x32_bf16 v[56:59], v[140:143], v[148:151], v[56:59]
	v_mfma_f32_16x16x32_bf16 v[44:47], v[132:135], v[172:175], v[44:47]
	v_mfma_f32_16x16x32_bf16 v[40:43], v[140:143], v[172:175], v[40:43]
	v_mfma_f32_16x16x32_bf16 v[28:31], v[132:135], v[180:183], v[28:31]
	v_mfma_f32_16x16x32_bf16 v[24:27], v[140:143], v[180:183], v[24:27]
	v_mfma_f32_16x16x32_bf16 v[12:15], v[132:135], v[196:199], v[12:15]
	v_mfma_f32_16x16x32_bf16 v[8:11], v[140:143], v[196:199], v[8:11]
	s_setprio 0
	s_barrier
	s_add_u32 s58, s42, 0x40000
	s_addc_u32 s59, s43, 0
	s_add_i32 s60, s53, s3
	v_lshl_add_u64 v[128:129], s[58:59], 0, v[154:155]
	s_mov_b32 m0, s60
	s_nop 0
	global_load_lds_dwordx4 v[128:129], off
	v_lshl_add_u64 v[128:129], s[58:59], 0, v[158:159]
	s_add_i32 m0, s60, 0x2000
	s_nop 0
	global_load_lds_dwordx4 v[128:129], off
	s_waitcnt vmcnt(6)
	s_barrier
	s_setprio 1
	v_mfma_f32_16x16x32_bf16 v[52:55], v[200:203], v[144:147], 0
	v_mfma_f32_16x16x32_bf16 v[48:51], v[210:213], v[144:147], 0
	v_mfma_f32_16x16x32_bf16 v[36:39], v[200:203], v[168:171], 0
	v_mfma_f32_16x16x32_bf16 v[32:35], v[210:213], v[168:171], 0
	v_mfma_f32_16x16x32_bf16 v[20:23], v[200:203], v[176:179], 0
	v_mfma_f32_16x16x32_bf16 v[16:19], v[210:213], v[176:179], 0
	v_mfma_f32_16x16x32_bf16 v[4:7], v[200:203], v[192:195], 0
	v_mfma_f32_16x16x32_bf16 v[0:3], v[210:213], v[192:195], 0
	v_mfma_f32_16x16x32_bf16 v[52:55], v[206:209], v[148:151], v[52:55]
	v_mfma_f32_16x16x32_bf16 v[48:51], v[214:217], v[148:151], v[48:51]
	v_mfma_f32_16x16x32_bf16 v[36:39], v[206:209], v[172:175], v[36:39]
	v_mfma_f32_16x16x32_bf16 v[32:35], v[214:217], v[172:175], v[32:35]
	v_mfma_f32_16x16x32_bf16 v[20:23], v[206:209], v[180:183], v[20:23]
	v_mfma_f32_16x16x32_bf16 v[16:19], v[214:217], v[180:183], v[16:19]
	v_mfma_f32_16x16x32_bf16 v[4:7], v[206:209], v[196:199], v[4:7]
	v_mfma_f32_16x16x32_bf16 v[0:3], v[214:217], v[196:199], v[0:3]
	s_setprio 0
	s_add_i32 s58, 0, 0x18000
	v_add_u32_e32 v140, s58, v187
	s_barrier
	ds_read_b128 v[128:131], v140
	ds_read_b128 v[132:135], v140 offset:1024
	ds_read_b128 v[136:139], v140 offset:2048
	ds_read_b128 v[140:143], v140 offset:3072
	s_add_u32 s44, s44, 0x40000
	s_addc_u32 s45, s45, 0
	s_mov_b32 m0, s33
	v_lshl_add_u64 v[200:201], s[44:45], 0, v[152:153]
	ds_read_b128 v[144:147], v190 offset:32768
	ds_read_b128 v[148:151], v190 offset:33792
	ds_read_b128 v[168:171], v190 offset:34816
	ds_read_b128 v[172:175], v190 offset:35840
	ds_read_b128 v[176:179], v190 offset:36864
	ds_read_b128 v[180:183], v190 offset:37888
	ds_read_b128 v[192:195], v190 offset:38912
	ds_read_b128 v[196:199], v190 offset:39936
	global_load_lds_dwordx4 v[200:201], off
	v_lshl_add_u64 v[200:201], s[44:45], 0, v[156:157]
	s_mov_b32 m0, s39
	s_nop 0
	global_load_lds_dwordx4 v[200:201], off
	s_waitcnt lgkmcnt(8)
	s_barrier
	s_waitcnt lgkmcnt(0)
	s_setprio 1
	s_waitcnt lgkmcnt(0)
	v_mfma_f32_16x16x32_bf16 v[124:127], v[128:131], v[144:147], v[124:127]
	v_mfma_f32_16x16x32_bf16 v[120:123], v[136:139], v[144:147], v[120:123]
	v_mfma_f32_16x16x32_bf16 v[108:111], v[128:131], v[168:171], v[108:111]
	v_mfma_f32_16x16x32_bf16 v[104:107], v[136:139], v[168:171], v[104:107]
	v_mfma_f32_16x16x32_bf16 v[92:95], v[128:131], v[176:179], v[92:95]
	v_mfma_f32_16x16x32_bf16 v[88:91], v[136:139], v[176:179], v[88:91]
	v_mfma_f32_16x16x32_bf16 v[76:79], v[128:131], v[192:195], v[76:79]
	v_mfma_f32_16x16x32_bf16 v[72:75], v[136:139], v[192:195], v[72:75]
	v_mfma_f32_16x16x32_bf16 v[124:127], v[132:135], v[148:151], v[124:127]
	v_mfma_f32_16x16x32_bf16 v[120:123], v[140:143], v[148:151], v[120:123]
	v_mfma_f32_16x16x32_bf16 v[108:111], v[132:135], v[172:175], v[108:111]
	v_mfma_f32_16x16x32_bf16 v[104:107], v[140:143], v[172:175], v[104:107]
	v_mfma_f32_16x16x32_bf16 v[92:95], v[132:135], v[180:183], v[92:95]
	v_mfma_f32_16x16x32_bf16 v[88:91], v[140:143], v[180:183], v[88:91]
	v_mfma_f32_16x16x32_bf16 v[76:79], v[132:135], v[196:199], v[76:79]
	v_mfma_f32_16x16x32_bf16 v[72:75], v[140:143], v[196:199], v[72:75]
	s_setprio 0
	s_barrier
	s_add_i32 s44, 0, 0x1c000
	s_add_i32 s45, s58, s3
	v_add_u32_e32 v214, s44, v187
	v_lshl_add_u64 v[184:185], v[184:185], 0, s[24:25]
	s_mov_b32 m0, s45
	ds_read_b128 v[200:203], v214
	ds_read_b128 v[206:209], v214 offset:1024
	ds_read_b128 v[210:213], v214 offset:2048
	ds_read_b128 v[214:217], v214 offset:3072
	global_load_lds_dwordx4 v[184:185], off
	v_lshl_add_u64 v[184:185], v[218:219], 0, s[24:25]
	s_add_i32 m0, s45, 0x2000
	s_nop 0
	global_load_lds_dwordx4 v[184:185], off
	s_barrier
	s_waitcnt lgkmcnt(0)
	s_setprio 1
	s_waitcnt lgkmcnt(0)
	v_mfma_f32_16x16x32_bf16 v[116:119], v[200:203], v[144:147], v[116:119]
	v_mfma_f32_16x16x32_bf16 v[112:115], v[210:213], v[144:147], v[112:115]
	v_mfma_f32_16x16x32_bf16 v[100:103], v[200:203], v[168:171], v[100:103]
	v_mfma_f32_16x16x32_bf16 v[96:99], v[210:213], v[168:171], v[96:99]
	v_mfma_f32_16x16x32_bf16 v[84:87], v[200:203], v[176:179], v[84:87]
	v_mfma_f32_16x16x32_bf16 v[80:83], v[210:213], v[176:179], v[80:83]
	v_mfma_f32_16x16x32_bf16 v[68:71], v[200:203], v[192:195], v[68:71]
	v_mfma_f32_16x16x32_bf16 v[64:67], v[210:213], v[192:195], v[64:67]
	v_mfma_f32_16x16x32_bf16 v[116:119], v[206:209], v[148:151], v[116:119]
	v_mfma_f32_16x16x32_bf16 v[112:115], v[214:217], v[148:151], v[112:115]
	v_mfma_f32_16x16x32_bf16 v[100:103], v[206:209], v[172:175], v[100:103]
	v_mfma_f32_16x16x32_bf16 v[96:99], v[214:217], v[172:175], v[96:99]
	v_mfma_f32_16x16x32_bf16 v[84:87], v[206:209], v[180:183], v[84:87]
	v_mfma_f32_16x16x32_bf16 v[80:83], v[214:217], v[180:183], v[80:83]
	v_mfma_f32_16x16x32_bf16 v[68:71], v[206:209], v[196:199], v[68:71]
	v_mfma_f32_16x16x32_bf16 v[64:67], v[214:217], v[196:199], v[64:67]
	s_setprio 0
	s_mov_b32 m0, s47
	v_lshl_add_u64 v[184:185], v[220:221], 0, s[24:25]
	s_barrier
	ds_read_b128 v[144:147], v190 offset:49152
	ds_read_b128 v[148:151], v190 offset:50176
	ds_read_b128 v[168:171], v190 offset:51200
	ds_read_b128 v[172:175], v190 offset:52224
	ds_read_b128 v[176:179], v190 offset:53248
	ds_read_b128 v[180:183], v190 offset:54272
	ds_read_b128 v[192:195], v190 offset:55296
	ds_read_b128 v[196:199], v190 offset:56320
	global_load_lds_dwordx4 v[184:185], off
	v_lshl_add_u64 v[184:185], v[222:223], 0, s[24:25]
	s_mov_b32 m0, s48
	s_nop 0
	global_load_lds_dwordx4 v[184:185], off
	s_barrier
	s_waitcnt lgkmcnt(0)
	s_setprio 1
	s_waitcnt lgkmcnt(0)
	v_mfma_f32_16x16x32_bf16 v[60:63], v[128:131], v[144:147], v[60:63]
	v_mfma_f32_16x16x32_bf16 v[56:59], v[136:139], v[144:147], v[56:59]
	v_mfma_f32_16x16x32_bf16 v[44:47], v[128:131], v[168:171], v[44:47]
	v_mfma_f32_16x16x32_bf16 v[40:43], v[136:139], v[168:171], v[40:43]
	v_mfma_f32_16x16x32_bf16 v[28:31], v[128:131], v[176:179], v[28:31]
	v_mfma_f32_16x16x32_bf16 v[24:27], v[136:139], v[176:179], v[24:27]
	v_mfma_f32_16x16x32_bf16 v[12:15], v[128:131], v[192:195], v[12:15]
	v_mfma_f32_16x16x32_bf16 v[8:11], v[136:139], v[192:195], v[8:11]
	v_mfma_f32_16x16x32_bf16 v[60:63], v[132:135], v[148:151], v[60:63]
	v_mfma_f32_16x16x32_bf16 v[56:59], v[140:143], v[148:151], v[56:59]
	v_mfma_f32_16x16x32_bf16 v[44:47], v[132:135], v[172:175], v[44:47]
	v_mfma_f32_16x16x32_bf16 v[40:43], v[140:143], v[172:175], v[40:43]
	v_mfma_f32_16x16x32_bf16 v[28:31], v[132:135], v[180:183], v[28:31]
	v_mfma_f32_16x16x32_bf16 v[24:27], v[140:143], v[180:183], v[24:27]
	v_mfma_f32_16x16x32_bf16 v[12:15], v[132:135], v[196:199], v[12:15]
	v_mfma_f32_16x16x32_bf16 v[8:11], v[140:143], v[196:199], v[8:11]
	s_setprio 0
	s_barrier
	s_add_u32 s42, s42, 0x40080
	s_addc_u32 s43, s43, 0
	s_add_i32 s44, s44, s3
	v_lshl_add_u64 v[128:129], s[42:43], 0, v[154:155]
	s_mov_b32 m0, s44
	s_nop 0
	global_load_lds_dwordx4 v[128:129], off
	v_lshl_add_u64 v[128:129], s[42:43], 0, v[158:159]
	s_add_i32 m0, s44, 0x2000
	s_nop 0
	global_load_lds_dwordx4 v[128:129], off
	s_waitcnt vmcnt(6)
	s_barrier
	s_setprio 1
	v_mfma_f32_16x16x32_bf16 v[52:55], v[200:203], v[144:147], v[52:55]
	v_mfma_f32_16x16x32_bf16 v[48:51], v[210:213], v[144:147], v[48:51]
	v_mfma_f32_16x16x32_bf16 v[36:39], v[200:203], v[168:171], v[36:39]
	v_mfma_f32_16x16x32_bf16 v[32:35], v[210:213], v[168:171], v[32:35]
	v_mfma_f32_16x16x32_bf16 v[20:23], v[200:203], v[176:179], v[20:23]
	v_mfma_f32_16x16x32_bf16 v[16:19], v[210:213], v[176:179], v[16:19]
	v_mfma_f32_16x16x32_bf16 v[4:7], v[200:203], v[192:195], v[4:7]
	v_mfma_f32_16x16x32_bf16 v[0:3], v[210:213], v[192:195], v[0:3]
	v_mfma_f32_16x16x32_bf16 v[52:55], v[206:209], v[148:151], v[52:55]
	v_mfma_f32_16x16x32_bf16 v[48:51], v[214:217], v[148:151], v[48:51]
	v_mfma_f32_16x16x32_bf16 v[36:39], v[206:209], v[172:175], v[36:39]
	v_mfma_f32_16x16x32_bf16 v[32:35], v[214:217], v[172:175], v[32:35]
	v_mfma_f32_16x16x32_bf16 v[20:23], v[206:209], v[180:183], v[20:23]
	v_mfma_f32_16x16x32_bf16 v[16:19], v[214:217], v[180:183], v[16:19]
	v_mfma_f32_16x16x32_bf16 v[4:7], v[206:209], v[196:199], v[4:7]
	v_mfma_f32_16x16x32_bf16 v[0:3], v[214:217], v[196:199], v[0:3]
	s_setprio 0
	s_add_i32 s57, s57, 2
	s_add_u32 s40, s40, 0x100
	s_addc_u32 s41, s41, 0
	s_add_u32 s55, s55, 0x100
	s_addc_u32 s56, s56, 0
	s_cmp_gt_u32 s57, 13
	s_barrier

.LBB0_1980:
	s_ashr_i32 s37, s36, 31
	v_cmp_lt_i64_e32 vcc, s[38:39], v[140:141]
	s_lshl_b64 s[38:39], s[36:37], 19
	s_add_u32 s38, s2, s38
	s_addc_u32 s39, s3, s39
	s_and_b64 s[40:41], vcc, exec
	s_cselect_b32 s9, s39, s11
	s_cselect_b32 s37, s38, s10
	s_ashr_i32 s35, s34, 31
	s_lshl_b64 s[40:41], s[34:35], 19
	s_add_u32 s40, s20, s40
	s_addc_u32 s41, s21, s41
	s_and_b64 s[44:45], vcc, exec
	s_cselect_b32 s35, s41, s43
	s_cselect_b32 s63, s40, s42
	s_add_u32 s10, s10, 0x40080
	s_addc_u32 s11, s11, 0
	s_add_u32 s64, s42, 0x100

	s_addc_u32 s65, s43, 0
	s_mov_b32 s66, -2


	ds_read_b128 v[164:167], v155
	ds_read_b128 v[168:171], v155 offset:1024
	ds_read_b128 v[172:175], v155 offset:2048
	ds_read_b128 v[176:179], v155 offset:3072
	s_add_u32 s42, s10, 0xfffc0080
	s_addc_u32 s43, s11, -1
	s_cmp_eq_u32 s66, 12
	s_cselect_b32 s45, s9, s43
	s_cselect_b32 s44, s37, s42
	s_cselect_b32 s43, s35, s65
	s_cselect_b32 s42, s63, s64
	v_lshl_add_u64 v[146:147], s[10:11], 0, v[136:137]
	s_add_i32 m0, s46, 0xc000
	ds_read_b128 v[180:183], v159
	ds_read_b128 v[184:187], v159 offset:1024
	ds_read_b128 v[188:191], v159 offset:2048
	ds_read_b128 v[192:195], v159 offset:3072
	ds_read_b128 v[196:199], v159 offset:4096
	ds_read_b128 v[200:203], v159 offset:5120
	ds_read_b128 v[206:209], v159 offset:6144
	ds_read_b128 v[210:213], v159 offset:7168
	global_load_lds_dwordx4 v[146:147], off
	v_lshl_add_u64 v[146:147], s[10:11], 0, v[138:139]
	s_add_i32 m0, s46, 0xe000
	s_nop 0
	global_load_lds_dwordx4 v[146:147], off
	s_waitcnt lgkmcnt(8)
	s_barrier
	s_waitcnt lgkmcnt(0)
	s_setprio 1
	s_waitcnt lgkmcnt(0)
	v_mfma_f32_16x16x32_bf16 v[124:127], v[164:167], v[180:183], 0
	v_mfma_f32_16x16x32_bf16 v[120:123], v[172:175], v[180:183], 0
	v_mfma_f32_16x16x32_bf16 v[108:111], v[164:167], v[188:191], 0
	v_mfma_f32_16x16x32_bf16 v[104:107], v[172:175], v[188:191], 0
	v_mfma_f32_16x16x32_bf16 v[92:95], v[164:167], v[196:199], 0
	v_mfma_f32_16x16x32_bf16 v[88:91], v[172:175], v[196:199], 0
	v_mfma_f32_16x16x32_bf16 v[76:79], v[164:167], v[206:209], 0
	v_mfma_f32_16x16x32_bf16 v[72:75], v[172:175], v[206:209], 0
	v_mfma_f32_16x16x32_bf16 v[124:127], v[168:171], v[184:187], v[124:127]
	v_mfma_f32_16x16x32_bf16 v[120:123], v[176:179], v[184:187], v[120:123]
	v_mfma_f32_16x16x32_bf16 v[108:111], v[168:171], v[192:195], v[108:111]
	v_mfma_f32_16x16x32_bf16 v[104:107], v[176:179], v[192:195], v[104:107]
	v_mfma_f32_16x16x32_bf16 v[92:95], v[168:171], v[200:203], v[92:95]
	v_mfma_f32_16x16x32_bf16 v[88:91], v[176:179], v[200:203], v[88:91]
	v_mfma_f32_16x16x32_bf16 v[76:79], v[168:171], v[210:213], v[76:79]
	v_mfma_f32_16x16x32_bf16 v[72:75], v[176:179], v[210:213], v[72:75]
	s_setprio 0
	s_barrier
	s_add_i32 s67, s55, s33
	v_lshl_add_u64 v[146:147], s[42:43], 0, v[130:131]
	s_mov_b32 m0, s67
	ds_read_b128 v[214:217], v162
	ds_read_b128 v[218:221], v162 offset:1024
	ds_read_b128 v[222:225], v162 offset:2048
	ds_read_b128 v[226:229], v162 offset:3072
	global_load_lds_dwordx4 v[146:147], off
	v_lshl_add_u64 v[152:153], s[42:43], 0, v[134:135]
	s_add_i32 m0, s67, 0x2000
	s_nop 0
	global_load_lds_dwordx4 v[152:153], off
	s_barrier
	s_waitcnt lgkmcnt(0)
	s_setprio 1
	s_waitcnt lgkmcnt(0)
	v_mfma_f32_16x16x32_bf16 v[116:119], v[214:217], v[180:183], 0
	v_mfma_f32_16x16x32_bf16 v[112:115], v[222:225], v[180:183], 0
	v_mfma_f32_16x16x32_bf16 v[100:103], v[214:217], v[188:191], 0
	v_mfma_f32_16x16x32_bf16 v[96:99], v[222:225], v[188:191], 0
	v_mfma_f32_16x16x32_bf16 v[84:87], v[214:217], v[196:199], 0
	v_mfma_f32_16x16x32_bf16 v[80:83], v[222:225], v[196:199], 0
	v_mfma_f32_16x16x32_bf16 v[68:71], v[214:217], v[206:209], 0
	v_mfma_f32_16x16x32_bf16 v[64:67], v[222:225], v[206:209], 0
	v_mfma_f32_16x16x32_bf16 v[116:119], v[218:221], v[184:187], v[116:119]
	v_mfma_f32_16x16x32_bf16 v[112:115], v[226:229], v[184:187], v[112:115]
	v_mfma_f32_16x16x32_bf16 v[100:103], v[218:221], v[192:195], v[100:103]
	v_mfma_f32_16x16x32_bf16 v[96:99], v[226:229], v[192:195], v[96:99]
	v_mfma_f32_16x16x32_bf16 v[84:87], v[218:221], v[200:203], v[84:87]
	v_mfma_f32_16x16x32_bf16 v[80:83], v[226:229], v[200:203], v[80:83]
	v_mfma_f32_16x16x32_bf16 v[68:71], v[218:221], v[210:213], v[68:71]
	v_mfma_f32_16x16x32_bf16 v[64:67], v[226:229], v[210:213], v[64:67]
	s_setprio 0
	s_mov_b32 m0, s46
	v_lshl_add_u64 v[156:157], s[44:45], 0, v[128:129]
	s_barrier
	ds_read_b128 v[180:183], v159 offset:16384
	ds_read_b128 v[184:187], v159 offset:17408
	ds_read_b128 v[188:191], v159 offset:18432
	ds_read_b128 v[192:195], v159 offset:19456
	ds_read_b128 v[196:199], v159 offset:20480
	ds_read_b128 v[200:203], v159 offset:21504
	ds_read_b128 v[206:209], v159 offset:22528
	ds_read_b128 v[210:213], v159 offset:23552
	global_load_lds_dwordx4 v[156:157], off
	v_lshl_add_u64 v[160:161], s[44:45], 0, v[132:133]
	s_mov_b32 m0, s47
	s_nop 0
	global_load_lds_dwordx4 v[160:161], off
	s_barrier
	s_waitcnt lgkmcnt(0)
	s_setprio 1
	s_waitcnt lgkmcnt(0)
	v_mfma_f32_16x16x32_bf16 v[60:63], v[164:167], v[180:183], 0
	v_mfma_f32_16x16x32_bf16 v[56:59], v[172:175], v[180:183], 0
	v_mfma_f32_16x16x32_bf16 v[44:47], v[164:167], v[188:191], 0
	v_mfma_f32_16x16x32_bf16 v[40:43], v[172:175], v[188:191], 0
	v_mfma_f32_16x16x32_bf16 v[28:31], v[164:167], v[196:199], 0
	v_mfma_f32_16x16x32_bf16 v[24:27], v[172:175], v[196:199], 0
	v_mfma_f32_16x16x32_bf16 v[12:15], v[164:167], v[206:209], 0
	v_mfma_f32_16x16x32_bf16 v[8:11], v[172:175], v[206:209], 0
	v_mfma_f32_16x16x32_bf16 v[60:63], v[168:171], v[184:187], v[60:63]
	v_mfma_f32_16x16x32_bf16 v[56:59], v[176:179], v[184:187], v[56:59]
	v_mfma_f32_16x16x32_bf16 v[44:47], v[168:171], v[192:195], v[44:47]
	v_mfma_f32_16x16x32_bf16 v[40:43], v[176:179], v[192:195], v[40:43]
	v_mfma_f32_16x16x32_bf16 v[28:31], v[168:171], v[200:203], v[28:31]
	v_mfma_f32_16x16x32_bf16 v[24:27], v[176:179], v[200:203], v[24:27]
	v_mfma_f32_16x16x32_bf16 v[12:15], v[168:171], v[210:213], v[12:15]
	v_mfma_f32_16x16x32_bf16 v[8:11], v[176:179], v[210:213], v[8:11]
	s_setprio 0
	s_barrier
	s_add_u32 s68, s42, 0x40000
	s_addc_u32 s69, s43, 0
	s_add_i32 s67, s56, s33
	v_lshl_add_u64 v[164:165], s[68:69], 0, v[130:131]
	s_mov_b32 m0, s67
	s_nop 0
	global_load_lds_dwordx4 v[164:165], off
	v_lshl_add_u64 v[164:165], s[68:69], 0, v[134:135]
	s_add_i32 m0, s67, 0x2000
	s_nop 0
	global_load_lds_dwordx4 v[164:165], off
	s_waitcnt vmcnt(6)
	s_barrier
	s_setprio 1
	v_mfma_f32_16x16x32_bf16 v[52:55], v[214:217], v[180:183], 0
	v_mfma_f32_16x16x32_bf16 v[48:51], v[222:225], v[180:183], 0
	v_mfma_f32_16x16x32_bf16 v[36:39], v[214:217], v[188:191], 0
	v_mfma_f32_16x16x32_bf16 v[32:35], v[222:225], v[188:191], 0
	v_mfma_f32_16x16x32_bf16 v[20:23], v[214:217], v[196:199], 0
	v_mfma_f32_16x16x32_bf16 v[16:19], v[222:225], v[196:199], 0
	v_mfma_f32_16x16x32_bf16 v[4:7], v[214:217], v[206:209], 0
	v_mfma_f32_16x16x32_bf16 v[0:3], v[222:225], v[206:209], 0
	v_mfma_f32_16x16x32_bf16 v[52:55], v[218:221], v[184:187], v[52:55]
	v_mfma_f32_16x16x32_bf16 v[48:51], v[226:229], v[184:187], v[48:51]
	v_mfma_f32_16x16x32_bf16 v[36:39], v[218:221], v[192:195], v[36:39]
	v_mfma_f32_16x16x32_bf16 v[32:35], v[226:229], v[192:195], v[32:35]
	v_mfma_f32_16x16x32_bf16 v[20:23], v[218:221], v[200:203], v[20:23]
	v_mfma_f32_16x16x32_bf16 v[16:19], v[226:229], v[200:203], v[16:19]
	v_mfma_f32_16x16x32_bf16 v[4:7], v[218:221], v[210:213], v[4:7]
	v_mfma_f32_16x16x32_bf16 v[0:3], v[226:229], v[210:213], v[0:3]
	s_setprio 0
	s_add_i32 s67, 0, 0x18000
	v_add_u32_e32 v144, s67, v149
	s_barrier
	ds_read_b128 v[164:167], v144
	ds_read_b128 v[168:171], v144 offset:1024
	ds_read_b128 v[172:175], v144 offset:2048
	ds_read_b128 v[176:179], v144 offset:3072
	s_add_u32 s44, s44, 0x40000
	s_addc_u32 s45, s45, 0
	s_mov_b32 m0, s48
	v_lshl_add_u64 v[214:215], s[44:45], 0, v[128:129]
	ds_read_b128 v[180:183], v159 offset:32768
	ds_read_b128 v[184:187], v159 offset:33792
	ds_read_b128 v[188:191], v159 offset:34816
	ds_read_b128 v[192:195], v159 offset:35840
	ds_read_b128 v[196:199], v159 offset:36864
	ds_read_b128 v[200:203], v159 offset:37888
	ds_read_b128 v[206:209], v159 offset:38912
	ds_read_b128 v[210:213], v159 offset:39936
	global_load_lds_dwordx4 v[214:215], off
	v_lshl_add_u64 v[214:215], s[44:45], 0, v[132:133]
	s_mov_b32 m0, s49
	s_nop 0
	global_load_lds_dwordx4 v[214:215], off
	s_waitcnt lgkmcnt(8)
	s_barrier
	s_waitcnt lgkmcnt(0)
	s_setprio 1
	s_waitcnt lgkmcnt(0)
	v_mfma_f32_16x16x32_bf16 v[124:127], v[164:167], v[180:183], v[124:127]
	v_mfma_f32_16x16x32_bf16 v[120:123], v[172:175], v[180:183], v[120:123]
	v_mfma_f32_16x16x32_bf16 v[108:111], v[164:167], v[188:191], v[108:111]
	v_mfma_f32_16x16x32_bf16 v[104:107], v[172:175], v[188:191], v[104:107]
	v_mfma_f32_16x16x32_bf16 v[92:95], v[164:167], v[196:199], v[92:95]
	v_mfma_f32_16x16x32_bf16 v[88:91], v[172:175], v[196:199], v[88:91]
	v_mfma_f32_16x16x32_bf16 v[76:79], v[164:167], v[206:209], v[76:79]
	v_mfma_f32_16x16x32_bf16 v[72:75], v[172:175], v[206:209], v[72:75]
	v_mfma_f32_16x16x32_bf16 v[124:127], v[168:171], v[184:187], v[124:127]
	v_mfma_f32_16x16x32_bf16 v[120:123], v[176:179], v[184:187], v[120:123]
	v_mfma_f32_16x16x32_bf16 v[108:111], v[168:171], v[192:195], v[108:111]
	v_mfma_f32_16x16x32_bf16 v[104:107], v[176:179], v[192:195], v[104:107]
	v_mfma_f32_16x16x32_bf16 v[92:95], v[168:171], v[200:203], v[92:95]
	v_mfma_f32_16x16x32_bf16 v[88:91], v[176:179], v[200:203], v[88:91]
	v_mfma_f32_16x16x32_bf16 v[76:79], v[168:171], v[210:213], v[76:79]
	v_mfma_f32_16x16x32_bf16 v[72:75], v[176:179], v[210:213], v[72:75]
	s_setprio 0
	s_barrier
	s_add_i32 s44, 0, 0x1c000
	s_add_i32 s45, s67, s33
	v_add_u32_e32 v144, s44, v149
	v_lshl_add_u64 v[146:147], v[146:147], 0, s[18:19]
	s_mov_b32 m0, s45
	ds_read_b128 v[214:217], v144
	ds_read_b128 v[218:221], v144 offset:1024
	ds_read_b128 v[222:225], v144 offset:2048
	ds_read_b128 v[226:229], v144 offset:3072
	global_load_lds_dwordx4 v[146:147], off
	v_lshl_add_u64 v[146:147], v[152:153], 0, s[18:19]
	s_add_i32 m0, s45, 0x2000
	s_nop 0
	global_load_lds_dwordx4 v[146:147], off
	s_barrier
	s_waitcnt lgkmcnt(0)
	s_setprio 1
	s_waitcnt lgkmcnt(0)
	v_mfma_f32_16x16x32_bf16 v[116:119], v[214:217], v[180:183], v[116:119]
	v_mfma_f32_16x16x32_bf16 v[112:115], v[222:225], v[180:183], v[112:115]
	v_mfma_f32_16x16x32_bf16 v[100:103], v[214:217], v[188:191], v[100:103]
	v_mfma_f32_16x16x32_bf16 v[96:99], v[222:225], v[188:191], v[96:99]
	v_mfma_f32_16x16x32_bf16 v[84:87], v[214:217], v[196:199], v[84:87]
	v_mfma_f32_16x16x32_bf16 v[80:83], v[222:225], v[196:199], v[80:83]
	v_mfma_f32_16x16x32_bf16 v[68:71], v[214:217], v[206:209], v[68:71]
	v_mfma_f32_16x16x32_bf16 v[64:67], v[222:225], v[206:209], v[64:67]
	v_mfma_f32_16x16x32_bf16 v[116:119], v[218:221], v[184:187], v[116:119]
	v_mfma_f32_16x16x32_bf16 v[112:115], v[226:229], v[184:187], v[112:115]
	v_mfma_f32_16x16x32_bf16 v[100:103], v[218:221], v[192:195], v[100:103]
	v_mfma_f32_16x16x32_bf16 v[96:99], v[226:229], v[192:195], v[96:99]
	v_mfma_f32_16x16x32_bf16 v[84:87], v[218:221], v[200:203], v[84:87]
	v_mfma_f32_16x16x32_bf16 v[80:83], v[226:229], v[200:203], v[80:83]
	v_mfma_f32_16x16x32_bf16 v[68:71], v[218:221], v[210:213], v[68:71]
	v_mfma_f32_16x16x32_bf16 v[64:67], v[226:229], v[210:213], v[64:67]
	s_setprio 0
	s_mov_b32 m0, s51
	v_lshl_add_u64 v[146:147], v[156:157], 0, s[18:19]
	s_barrier
	ds_read_b128 v[180:183], v159 offset:49152
	ds_read_b128 v[184:187], v159 offset:50176
	ds_read_b128 v[188:191], v159 offset:51200
	ds_read_b128 v[192:195], v159 offset:52224
	ds_read_b128 v[196:199], v159 offset:53248
	ds_read_b128 v[200:203], v159 offset:54272
	ds_read_b128 v[206:209], v159 offset:55296
	ds_read_b128 v[210:213], v159 offset:56320
	global_load_lds_dwordx4 v[146:147], off
	v_lshl_add_u64 v[146:147], v[160:161], 0, s[18:19]
	s_mov_b32 m0, s52
	s_nop 0
	global_load_lds_dwordx4 v[146:147], off
	s_barrier
	s_waitcnt lgkmcnt(0)
	s_setprio 1
	s_waitcnt lgkmcnt(0)
	v_mfma_f32_16x16x32_bf16 v[60:63], v[164:167], v[180:183], v[60:63]
	v_mfma_f32_16x16x32_bf16 v[56:59], v[172:175], v[180:183], v[56:59]
	v_mfma_f32_16x16x32_bf16 v[44:47], v[164:167], v[188:191], v[44:47]
	v_mfma_f32_16x16x32_bf16 v[40:43], v[172:175], v[188:191], v[40:43]
	v_mfma_f32_16x16x32_bf16 v[28:31], v[164:167], v[196:199], v[28:31]
	v_mfma_f32_16x16x32_bf16 v[24:27], v[172:175], v[196:199], v[24:27]
	v_mfma_f32_16x16x32_bf16 v[12:15], v[164:167], v[206:209], v[12:15]
	v_mfma_f32_16x16x32_bf16 v[8:11], v[172:175], v[206:209], v[8:11]
	v_mfma_f32_16x16x32_bf16 v[60:63], v[168:171], v[184:187], v[60:63]
	v_mfma_f32_16x16x32_bf16 v[56:59], v[176:179], v[184:187], v[56:59]
	v_mfma_f32_16x16x32_bf16 v[44:47], v[168:171], v[192:195], v[44:47]
	v_mfma_f32_16x16x32_bf16 v[40:43], v[176:179], v[192:195], v[40:43]
	v_mfma_f32_16x16x32_bf16 v[28:31], v[168:171], v[200:203], v[28:31]
	v_mfma_f32_16x16x32_bf16 v[24:27], v[176:179], v[200:203], v[24:27]
	v_mfma_f32_16x16x32_bf16 v[12:15], v[168:171], v[210:213], v[12:15]
	v_mfma_f32_16x16x32_bf16 v[8:11], v[176:179], v[210:213], v[8:11]
	s_setprio 0
	s_barrier
	s_add_u32 s42, s42, 0x40080
	s_addc_u32 s43, s43, 0
	s_add_i32 s44, s44, s33
	v_lshl_add_u64 v[146:147], s[42:43], 0, v[130:131]
	s_mov_b32 m0, s44
	s_nop 0
	global_load_lds_dwordx4 v[146:147], off
	v_lshl_add_u64 v[146:147], s[42:43], 0, v[134:135]
	s_add_i32 m0, s44, 0x2000
	s_nop 0
	global_load_lds_dwordx4 v[146:147], off
	s_waitcnt vmcnt(6)
	s_barrier
	s_setprio 1
	v_mfma_f32_16x16x32_bf16 v[52:55], v[214:217], v[180:183], v[52:55]
	v_mfma_f32_16x16x32_bf16 v[48:51], v[222:225], v[180:183], v[48:51]
	v_mfma_f32_16x16x32_bf16 v[36:39], v[214:217], v[188:191], v[36:39]
	v_mfma_f32_16x16x32_bf16 v[32:35], v[222:225], v[188:191], v[32:35]
	v_mfma_f32_16x16x32_bf16 v[20:23], v[214:217], v[196:199], v[20:23]
	v_mfma_f32_16x16x32_bf16 v[16:19], v[222:225], v[196:199], v[16:19]
	v_mfma_f32_16x16x32_bf16 v[4:7], v[214:217], v[206:209], v[4:7]
	v_mfma_f32_16x16x32_bf16 v[0:3], v[222:225], v[206:209], v[0:3]
	v_mfma_f32_16x16x32_bf16 v[52:55], v[218:221], v[184:187], v[52:55]
	v_mfma_f32_16x16x32_bf16 v[48:51], v[226:229], v[184:187], v[48:51]
	v_mfma_f32_16x16x32_bf16 v[36:39], v[218:221], v[192:195], v[36:39]
	v_mfma_f32_16x16x32_bf16 v[32:35], v[226:229], v[192:195], v[32:35]
	v_mfma_f32_16x16x32_bf16 v[20:23], v[218:221], v[200:203], v[20:23]
	v_mfma_f32_16x16x32_bf16 v[16:19], v[226:229], v[200:203], v[16:19]
	v_mfma_f32_16x16x32_bf16 v[4:7], v[218:221], v[210:213], v[4:7]
	v_mfma_f32_16x16x32_bf16 v[0:3], v[226:229], v[210:213], v[0:3]
	s_setprio 0
	s_add_i32 s66, s66, 2
	s_add_u32 s10, s10, 0x100
	s_addc_u32 s11, s11, 0
	s_add_u32 s64, s64, 0x100
	s_addc_u32 s65, s65, 0
	s_cmp_gt_u32 s66, 13
	s_barrier

.LBB0_2055:
	s_ashr_i32 s19, s18, 31
	v_cmp_lt_i64_e32 vcc, s[24:25], v[164:165]
	s_lshl_b64 s[24:25], s[18:19], 21
	s_add_u32 s24, s1, s24
	s_addc_u32 s25, s2, s25
	s_and_b64 s[26:27], vcc, exec
	s_cselect_b32 s19, s25, s35
	s_cselect_b32 s29, s24, s34
	s_ashr_i32 s17, s16, 31
	s_lshl_b64 s[26:27], s[16:17], 21
	s_add_u32 s26, s3, s26
	s_addc_u32 s27, s20, s27
	s_and_b64 s[38:39], vcc, exec
	s_cselect_b32 s17, s27, s37
	s_cselect_b32 s50, s26, s36
	s_add_u32 s34, s34, 0x100080
	s_addc_u32 s35, s35, 0
	s_add_u32 s51, s36, 0x100

	s_addc_u32 s52, s37, 0
	s_mov_b32 s53, -2
	s_waitcnt lgkmcnt(0)


	ds_read_b128 v[128:131], v189
	ds_read_b128 v[132:135], v189 offset:1024
	ds_read_b128 v[136:139], v189 offset:2048
	ds_read_b128 v[140:143], v189 offset:3072
	s_add_u32 s36, s34, 0xfff00080
	s_addc_u32 s37, s35, -1
	s_cmp_eq_u32 s53, 60
	s_cselect_b32 s39, s19, s37
	s_cselect_b32 s38, s29, s36
	s_cselect_b32 s37, s17, s52
	s_cselect_b32 s36, s50, s51
	v_lshl_add_u64 v[184:185], s[34:35], 0, v[160:161]
	s_add_i32 m0, s31, 0xc000
	ds_read_b128 v[144:147], v190
	ds_read_b128 v[148:151], v190 offset:1024
	ds_read_b128 v[168:171], v190 offset:2048
	ds_read_b128 v[172:175], v190 offset:3072
	ds_read_b128 v[176:179], v190 offset:4096
	ds_read_b128 v[180:183], v190 offset:5120
	ds_read_b128 v[192:195], v190 offset:6144
	ds_read_b128 v[196:199], v190 offset:7168
	global_load_lds_dwordx4 v[184:185], off
	v_lshl_add_u64 v[184:185], s[34:35], 0, v[162:163]
	s_add_i32 m0, s31, 0xe000
	s_nop 0
	global_load_lds_dwordx4 v[184:185], off
	s_waitcnt lgkmcnt(8)
	s_barrier
	s_waitcnt lgkmcnt(0)
	s_setprio 1
	s_waitcnt lgkmcnt(0)
	v_mfma_f32_16x16x32_bf16 v[124:127], v[128:131], v[144:147], 0
	v_mfma_f32_16x16x32_bf16 v[120:123], v[136:139], v[144:147], 0
	v_mfma_f32_16x16x32_bf16 v[108:111], v[128:131], v[168:171], 0
	v_mfma_f32_16x16x32_bf16 v[104:107], v[136:139], v[168:171], 0
	v_mfma_f32_16x16x32_bf16 v[92:95], v[128:131], v[176:179], 0
	v_mfma_f32_16x16x32_bf16 v[88:91], v[136:139], v[176:179], 0
	v_mfma_f32_16x16x32_bf16 v[76:79], v[128:131], v[192:195], 0
	v_mfma_f32_16x16x32_bf16 v[72:75], v[136:139], v[192:195], 0
	v_mfma_f32_16x16x32_bf16 v[124:127], v[132:135], v[148:151], v[124:127]
	v_mfma_f32_16x16x32_bf16 v[120:123], v[140:143], v[148:151], v[120:123]
	v_mfma_f32_16x16x32_bf16 v[108:111], v[132:135], v[172:175], v[108:111]
	v_mfma_f32_16x16x32_bf16 v[104:107], v[140:143], v[172:175], v[104:107]
	v_mfma_f32_16x16x32_bf16 v[92:95], v[132:135], v[180:183], v[92:95]
	v_mfma_f32_16x16x32_bf16 v[88:91], v[140:143], v[180:183], v[88:91]
	v_mfma_f32_16x16x32_bf16 v[76:79], v[132:135], v[196:199], v[76:79]
	v_mfma_f32_16x16x32_bf16 v[72:75], v[140:143], v[196:199], v[72:75]
	s_setprio 0
	s_barrier
	s_add_i32 s54, s48, s21
	v_lshl_add_u64 v[184:185], s[36:37], 0, v[154:155]
	s_mov_b32 m0, s54
	ds_read_b128 v[200:203], v191
	ds_read_b128 v[206:209], v191 offset:1024
	ds_read_b128 v[210:213], v191 offset:2048
	ds_read_b128 v[214:217], v191 offset:3072
	global_load_lds_dwordx4 v[184:185], off
	v_lshl_add_u64 v[218:219], s[36:37], 0, v[158:159]
	s_add_i32 m0, s54, 0x2000
	s_nop 0
	global_load_lds_dwordx4 v[218:219], off
	s_barrier
	s_waitcnt lgkmcnt(0)
	s_setprio 1
	s_waitcnt lgkmcnt(0)
	v_mfma_f32_16x16x32_bf16 v[116:119], v[200:203], v[144:147], 0
	v_mfma_f32_16x16x32_bf16 v[112:115], v[210:213], v[144:147], 0
	v_mfma_f32_16x16x32_bf16 v[100:103], v[200:203], v[168:171], 0
	v_mfma_f32_16x16x32_bf16 v[96:99], v[210:213], v[168:171], 0
	v_mfma_f32_16x16x32_bf16 v[84:87], v[200:203], v[176:179], 0
	v_mfma_f32_16x16x32_bf16 v[80:83], v[210:213], v[176:179], 0
	v_mfma_f32_16x16x32_bf16 v[68:71], v[200:203], v[192:195], 0
	v_mfma_f32_16x16x32_bf16 v[64:67], v[210:213], v[192:195], 0
	v_mfma_f32_16x16x32_bf16 v[116:119], v[206:209], v[148:151], v[116:119]
	v_mfma_f32_16x16x32_bf16 v[112:115], v[214:217], v[148:151], v[112:115]
	v_mfma_f32_16x16x32_bf16 v[100:103], v[206:209], v[172:175], v[100:103]
	v_mfma_f32_16x16x32_bf16 v[96:99], v[214:217], v[172:175], v[96:99]
	v_mfma_f32_16x16x32_bf16 v[84:87], v[206:209], v[180:183], v[84:87]
	v_mfma_f32_16x16x32_bf16 v[80:83], v[214:217], v[180:183], v[80:83]
	v_mfma_f32_16x16x32_bf16 v[68:71], v[206:209], v[196:199], v[68:71]
	v_mfma_f32_16x16x32_bf16 v[64:67], v[214:217], v[196:199], v[64:67]
	s_setprio 0
	s_mov_b32 m0, s31
	v_lshl_add_u64 v[220:221], s[38:39], 0, v[152:153]
	s_barrier
	ds_read_b128 v[144:147], v190 offset:16384
	ds_read_b128 v[148:151], v190 offset:17408
	ds_read_b128 v[168:171], v190 offset:18432
	ds_read_b128 v[172:175], v190 offset:19456
	ds_read_b128 v[176:179], v190 offset:20480
	ds_read_b128 v[180:183], v190 offset:21504
	ds_read_b128 v[192:195], v190 offset:22528
	ds_read_b128 v[196:199], v190 offset:23552
	global_load_lds_dwordx4 v[220:221], off
	v_lshl_add_u64 v[222:223], s[38:39], 0, v[156:157]
	s_mov_b32 m0, s33
	s_nop 0
	global_load_lds_dwordx4 v[222:223], off
	s_barrier
	s_waitcnt lgkmcnt(0)
	s_setprio 1
	s_waitcnt lgkmcnt(0)
	v_mfma_f32_16x16x32_bf16 v[60:63], v[128:131], v[144:147], 0
	v_mfma_f32_16x16x32_bf16 v[56:59], v[136:139], v[144:147], 0
	v_mfma_f32_16x16x32_bf16 v[44:47], v[128:131], v[168:171], 0
	v_mfma_f32_16x16x32_bf16 v[40:43], v[136:139], v[168:171], 0
	v_mfma_f32_16x16x32_bf16 v[28:31], v[128:131], v[176:179], 0
	v_mfma_f32_16x16x32_bf16 v[24:27], v[136:139], v[176:179], 0
	v_mfma_f32_16x16x32_bf16 v[12:15], v[128:131], v[192:195], 0
	v_mfma_f32_16x16x32_bf16 v[8:11], v[136:139], v[192:195], 0
	v_mfma_f32_16x16x32_bf16 v[60:63], v[132:135], v[148:151], v[60:63]
	v_mfma_f32_16x16x32_bf16 v[56:59], v[140:143], v[148:151], v[56:59]
	v_mfma_f32_16x16x32_bf16 v[44:47], v[132:135], v[172:175], v[44:47]
	v_mfma_f32_16x16x32_bf16 v[40:43], v[140:143], v[172:175], v[40:43]
	v_mfma_f32_16x16x32_bf16 v[28:31], v[132:135], v[180:183], v[28:31]
	v_mfma_f32_16x16x32_bf16 v[24:27], v[140:143], v[180:183], v[24:27]
	v_mfma_f32_16x16x32_bf16 v[12:15], v[132:135], v[196:199], v[12:15]
	v_mfma_f32_16x16x32_bf16 v[8:11], v[140:143], v[196:199], v[8:11]
	s_setprio 0
	s_barrier
	s_add_u32 s54, s36, 0x100000
	s_addc_u32 s55, s37, 0
	s_add_i32 s56, s49, s21
	v_lshl_add_u64 v[128:129], s[54:55], 0, v[154:155]
	s_mov_b32 m0, s56
	s_nop 0
	global_load_lds_dwordx4 v[128:129], off
	v_lshl_add_u64 v[128:129], s[54:55], 0, v[158:159]
	s_add_i32 m0, s56, 0x2000
	s_nop 0
	global_load_lds_dwordx4 v[128:129], off
	s_waitcnt vmcnt(6)
	s_barrier
	s_setprio 1
	v_mfma_f32_16x16x32_bf16 v[52:55], v[200:203], v[144:147], 0
	v_mfma_f32_16x16x32_bf16 v[48:51], v[210:213], v[144:147], 0
	v_mfma_f32_16x16x32_bf16 v[36:39], v[200:203], v[168:171], 0
	v_mfma_f32_16x16x32_bf16 v[32:35], v[210:213], v[168:171], 0
	v_mfma_f32_16x16x32_bf16 v[20:23], v[200:203], v[176:179], 0
	v_mfma_f32_16x16x32_bf16 v[16:19], v[210:213], v[176:179], 0
	v_mfma_f32_16x16x32_bf16 v[4:7], v[200:203], v[192:195], 0
	v_mfma_f32_16x16x32_bf16 v[0:3], v[210:213], v[192:195], 0
	v_mfma_f32_16x16x32_bf16 v[52:55], v[206:209], v[148:151], v[52:55]
	v_mfma_f32_16x16x32_bf16 v[48:51], v[214:217], v[148:151], v[48:51]
	v_mfma_f32_16x16x32_bf16 v[36:39], v[206:209], v[172:175], v[36:39]
	v_mfma_f32_16x16x32_bf16 v[32:35], v[214:217], v[172:175], v[32:35]
	v_mfma_f32_16x16x32_bf16 v[20:23], v[206:209], v[180:183], v[20:23]
	v_mfma_f32_16x16x32_bf16 v[16:19], v[214:217], v[180:183], v[16:19]
	v_mfma_f32_16x16x32_bf16 v[4:7], v[206:209], v[196:199], v[4:7]
	v_mfma_f32_16x16x32_bf16 v[0:3], v[214:217], v[196:199], v[0:3]
	s_setprio 0
	s_add_i32 s54, 0, 0x18000
	v_add_u32_e32 v140, s54, v187
	s_barrier
	ds_read_b128 v[128:131], v140
	ds_read_b128 v[132:135], v140 offset:1024
	ds_read_b128 v[136:139], v140 offset:2048
	ds_read_b128 v[140:143], v140 offset:3072
	s_add_u32 s38, s38, 0x100000
	s_addc_u32 s39, s39, 0
	s_mov_b32 m0, s40
	v_lshl_add_u64 v[200:201], s[38:39], 0, v[152:153]
	ds_read_b128 v[144:147], v190 offset:32768
	ds_read_b128 v[148:151], v190 offset:33792
	ds_read_b128 v[168:171], v190 offset:34816
	ds_read_b128 v[172:175], v190 offset:35840
	ds_read_b128 v[176:179], v190 offset:36864
	ds_read_b128 v[180:183], v190 offset:37888
	ds_read_b128 v[192:195], v190 offset:38912
	ds_read_b128 v[196:199], v190 offset:39936
	global_load_lds_dwordx4 v[200:201], off
	v_lshl_add_u64 v[200:201], s[38:39], 0, v[156:157]
	s_mov_b32 m0, s41
	s_nop 0
	global_load_lds_dwordx4 v[200:201], off
	s_waitcnt lgkmcnt(8)
	s_barrier
	s_waitcnt lgkmcnt(0)
	s_setprio 1
	s_waitcnt lgkmcnt(0)
	v_mfma_f32_16x16x32_bf16 v[124:127], v[128:131], v[144:147], v[124:127]
	v_mfma_f32_16x16x32_bf16 v[120:123], v[136:139], v[144:147], v[120:123]
	v_mfma_f32_16x16x32_bf16 v[108:111], v[128:131], v[168:171], v[108:111]
	v_mfma_f32_16x16x32_bf16 v[104:107], v[136:139], v[168:171], v[104:107]
	v_mfma_f32_16x16x32_bf16 v[92:95], v[128:131], v[176:179], v[92:95]
	v_mfma_f32_16x16x32_bf16 v[88:91], v[136:139], v[176:179], v[88:91]
	v_mfma_f32_16x16x32_bf16 v[76:79], v[128:131], v[192:195], v[76:79]
	v_mfma_f32_16x16x32_bf16 v[72:75], v[136:139], v[192:195], v[72:75]
	v_mfma_f32_16x16x32_bf16 v[124:127], v[132:135], v[148:151], v[124:127]
	v_mfma_f32_16x16x32_bf16 v[120:123], v[140:143], v[148:151], v[120:123]
	v_mfma_f32_16x16x32_bf16 v[108:111], v[132:135], v[172:175], v[108:111]
	v_mfma_f32_16x16x32_bf16 v[104:107], v[140:143], v[172:175], v[104:107]
	v_mfma_f32_16x16x32_bf16 v[92:95], v[132:135], v[180:183], v[92:95]
	v_mfma_f32_16x16x32_bf16 v[88:91], v[140:143], v[180:183], v[88:91]
	v_mfma_f32_16x16x32_bf16 v[76:79], v[132:135], v[196:199], v[76:79]
	v_mfma_f32_16x16x32_bf16 v[72:75], v[140:143], v[196:199], v[72:75]
	s_setprio 0
	s_barrier
	s_add_i32 s38, 0, 0x1c000
	s_add_i32 s39, s54, s21
	v_add_u32_e32 v214, s38, v187
	v_lshl_add_u64 v[184:185], v[184:185], 0, s[14:15]
	s_mov_b32 m0, s39
	ds_read_b128 v[200:203], v214
	ds_read_b128 v[206:209], v214 offset:1024
	ds_read_b128 v[210:213], v214 offset:2048
	ds_read_b128 v[214:217], v214 offset:3072
	global_load_lds_dwordx4 v[184:185], off
	v_lshl_add_u64 v[184:185], v[218:219], 0, s[14:15]
	s_add_i32 m0, s39, 0x2000
	s_nop 0
	global_load_lds_dwordx4 v[184:185], off
	s_barrier
	s_waitcnt lgkmcnt(0)
	s_setprio 1
	s_waitcnt lgkmcnt(0)
	v_mfma_f32_16x16x32_bf16 v[116:119], v[200:203], v[144:147], v[116:119]
	v_mfma_f32_16x16x32_bf16 v[112:115], v[210:213], v[144:147], v[112:115]
	v_mfma_f32_16x16x32_bf16 v[100:103], v[200:203], v[168:171], v[100:103]
	v_mfma_f32_16x16x32_bf16 v[96:99], v[210:213], v[168:171], v[96:99]
	v_mfma_f32_16x16x32_bf16 v[84:87], v[200:203], v[176:179], v[84:87]
	v_mfma_f32_16x16x32_bf16 v[80:83], v[210:213], v[176:179], v[80:83]
	v_mfma_f32_16x16x32_bf16 v[68:71], v[200:203], v[192:195], v[68:71]
	v_mfma_f32_16x16x32_bf16 v[64:67], v[210:213], v[192:195], v[64:67]
	v_mfma_f32_16x16x32_bf16 v[116:119], v[206:209], v[148:151], v[116:119]
	v_mfma_f32_16x16x32_bf16 v[112:115], v[214:217], v[148:151], v[112:115]
	v_mfma_f32_16x16x32_bf16 v[100:103], v[206:209], v[172:175], v[100:103]
	v_mfma_f32_16x16x32_bf16 v[96:99], v[214:217], v[172:175], v[96:99]
	v_mfma_f32_16x16x32_bf16 v[84:87], v[206:209], v[180:183], v[84:87]
	v_mfma_f32_16x16x32_bf16 v[80:83], v[214:217], v[180:183], v[80:83]
	v_mfma_f32_16x16x32_bf16 v[68:71], v[206:209], v[196:199], v[68:71]
	v_mfma_f32_16x16x32_bf16 v[64:67], v[214:217], v[196:199], v[64:67]
	s_setprio 0
	s_mov_b32 m0, s43
	v_lshl_add_u64 v[184:185], v[220:221], 0, s[14:15]
	s_barrier
	ds_read_b128 v[144:147], v190 offset:49152
	ds_read_b128 v[148:151], v190 offset:50176
	ds_read_b128 v[168:171], v190 offset:51200
	ds_read_b128 v[172:175], v190 offset:52224
	ds_read_b128 v[176:179], v190 offset:53248
	ds_read_b128 v[180:183], v190 offset:54272
	ds_read_b128 v[192:195], v190 offset:55296
	ds_read_b128 v[196:199], v190 offset:56320
	global_load_lds_dwordx4 v[184:185], off
	v_lshl_add_u64 v[184:185], v[222:223], 0, s[14:15]
	s_mov_b32 m0, s44
	s_nop 0
	global_load_lds_dwordx4 v[184:185], off
	s_barrier
	s_waitcnt lgkmcnt(0)
	s_setprio 1
	s_waitcnt lgkmcnt(0)
	v_mfma_f32_16x16x32_bf16 v[60:63], v[128:131], v[144:147], v[60:63]
	v_mfma_f32_16x16x32_bf16 v[56:59], v[136:139], v[144:147], v[56:59]
	v_mfma_f32_16x16x32_bf16 v[44:47], v[128:131], v[168:171], v[44:47]
	v_mfma_f32_16x16x32_bf16 v[40:43], v[136:139], v[168:171], v[40:43]
	v_mfma_f32_16x16x32_bf16 v[28:31], v[128:131], v[176:179], v[28:31]
	v_mfma_f32_16x16x32_bf16 v[24:27], v[136:139], v[176:179], v[24:27]
	v_mfma_f32_16x16x32_bf16 v[12:15], v[128:131], v[192:195], v[12:15]
	v_mfma_f32_16x16x32_bf16 v[8:11], v[136:139], v[192:195], v[8:11]
	v_mfma_f32_16x16x32_bf16 v[60:63], v[132:135], v[148:151], v[60:63]
	v_mfma_f32_16x16x32_bf16 v[56:59], v[140:143], v[148:151], v[56:59]
	v_mfma_f32_16x16x32_bf16 v[44:47], v[132:135], v[172:175], v[44:47]
	v_mfma_f32_16x16x32_bf16 v[40:43], v[140:143], v[172:175], v[40:43]
	v_mfma_f32_16x16x32_bf16 v[28:31], v[132:135], v[180:183], v[28:31]
	v_mfma_f32_16x16x32_bf16 v[24:27], v[140:143], v[180:183], v[24:27]
	v_mfma_f32_16x16x32_bf16 v[12:15], v[132:135], v[196:199], v[12:15]
	v_mfma_f32_16x16x32_bf16 v[8:11], v[140:143], v[196:199], v[8:11]
	s_setprio 0
	s_barrier
	s_add_u32 s36, s36, 0x100080
	s_addc_u32 s37, s37, 0
	s_add_i32 s38, s38, s21
	v_lshl_add_u64 v[128:129], s[36:37], 0, v[154:155]
	s_mov_b32 m0, s38
	s_nop 0
	global_load_lds_dwordx4 v[128:129], off
	v_lshl_add_u64 v[128:129], s[36:37], 0, v[158:159]
	s_add_i32 m0, s38, 0x2000
	s_nop 0
	global_load_lds_dwordx4 v[128:129], off
	s_waitcnt vmcnt(6)
	s_barrier
	s_setprio 1
	v_mfma_f32_16x16x32_bf16 v[52:55], v[200:203], v[144:147], v[52:55]
	v_mfma_f32_16x16x32_bf16 v[48:51], v[210:213], v[144:147], v[48:51]
	v_mfma_f32_16x16x32_bf16 v[36:39], v[200:203], v[168:171], v[36:39]
	v_mfma_f32_16x16x32_bf16 v[32:35], v[210:213], v[168:171], v[32:35]
	v_mfma_f32_16x16x32_bf16 v[20:23], v[200:203], v[176:179], v[20:23]
	v_mfma_f32_16x16x32_bf16 v[16:19], v[210:213], v[176:179], v[16:19]
	v_mfma_f32_16x16x32_bf16 v[4:7], v[200:203], v[192:195], v[4:7]
	v_mfma_f32_16x16x32_bf16 v[0:3], v[210:213], v[192:195], v[0:3]
	v_mfma_f32_16x16x32_bf16 v[52:55], v[206:209], v[148:151], v[52:55]
	v_mfma_f32_16x16x32_bf16 v[48:51], v[214:217], v[148:151], v[48:51]
	v_mfma_f32_16x16x32_bf16 v[36:39], v[206:209], v[172:175], v[36:39]
	v_mfma_f32_16x16x32_bf16 v[32:35], v[214:217], v[172:175], v[32:35]
	v_mfma_f32_16x16x32_bf16 v[20:23], v[206:209], v[180:183], v[20:23]
	v_mfma_f32_16x16x32_bf16 v[16:19], v[214:217], v[180:183], v[16:19]
	v_mfma_f32_16x16x32_bf16 v[4:7], v[206:209], v[196:199], v[4:7]
	v_mfma_f32_16x16x32_bf16 v[0:3], v[214:217], v[196:199], v[0:3]
	s_setprio 0
	s_add_i32 s53, s53, 2
	s_add_u32 s34, s34, 0x100
	s_addc_u32 s35, s35, 0
	s_add_u32 s51, s51, 0x100
	s_addc_u32 s52, s52, 0
	s_cmp_gt_u32 s53, 61
	s_barrier
